# Top-13 block selection rewritten: DPP row max + ds_swizzle + permlane32_swap, 4 tokens interleaved (same keys and tie-breaking), on top of the rewritten block loops
# speedup vs baseline: 1.0273x; 1.0273x over previous
; #define LAS __attribute__((address_space(3)))
; __device__ __forceinline__ void nsa_quad_pre(int bg, int quad, const bf16_t* Q, const bf16_t* KV, const bf16_t* KCMP, const bf16_t* VCMPT, const float* GN, bf16_t* ONSA, ...
;     ...
; #pragma unroll
;     for (int tt = 0; tt < 4; ++tt) {
;         const int tok = t0 + tt, cur = tok >> 6;
;         if (cur < 16) { if (lane < 16) selq[tt * 16 + lane] = lane; }
;         else {
;             unsigned k0 = 0u, k1 = 0u;
;             { const int j = lane; if (j >= 1 && j <= cur - 2) { const LAS float* ps = psum + tt * 512 + 4 * j - 1; const float v = ps[0] + ps[1] + ps[2] + ps[3] + ps[4]; k0 = (__builtin_bit_cast(unsigned, v) & ~127u) | (unsigned)(127 - j); } }
;             { const int j = lane + 64; if (j <= cur - 2) { const LAS float* ps = psum + tt * 512 + 4 * j - 1; const float v = ps[0] + ps[1] + ps[2] + ps[3] + ps[4]; k1 = (__builtin_bit_cast(unsigned, v) & ~127u) | (unsigned)(127 - j); } }
;             for (int it = 0; it < 13; ++it) {
;                 unsigned m = k0 > k1 ? k0 : k1;
; #pragma unroll
;                 for (int off = 32; off >= 1; off >>= 1) { const unsigned o = (unsigned)__shfl_xor((int)m, off); m = o > m ? o : m; }
;                 if (k0 == m) k0 = 0u; if (k1 == m) k1 = 0u;
;                 if (lane == 0) selq[tt * 16 + it] = 127 - (int)(m & 127u);
.LBB0_844:
	s_waitcnt lgkmcnt(0)
	s_cmp_gt_i32 s18, 15
	s_cbranch_scc0 .Ltopk_small_q0
	s_lshl_b32 s19, s80, 10
	s_add_i32 s19, s19, 56384
	v_lshlrev_b32_e32 v82, 4, v184
	v_add_u32_e32 v82, s19, v82
	v_add_u32_e32 v83, 0xfffffffc, v82
	v_sub_u32_e32 v80, 127, v184
	v_sub_u32_e32 v81, 63, v184
	s_mov_b32 s54, 0xffffff80
	s_add_i32 s21, s18, -2
	v_add_u32_e32 v84, 64, v184
	ds_read_b32 v40, v83 offset:0
	ds_read_b128 v[48:51], v82 offset:0
	ds_read_b32 v41, v83 offset:1024
	ds_read_b128 v[52:55], v82 offset:1024
	ds_read_b32 v42, v83 offset:2048
	ds_read_b128 v[56:59], v82 offset:2048
	ds_read_b32 v43, v83 offset:3072
	ds_read_b128 v[60:63], v82 offset:3072
	s_waitcnt lgkmcnt(6)
	v_add_f32_e32 v40, v40, v48
	v_add_f32_e32 v40, v40, v49
	v_add_f32_e32 v40, v40, v50
	v_add_f32_e32 v40, v40, v51
	v_and_or_b32 v20, v40, s54, v80
	s_waitcnt lgkmcnt(4)
	v_add_f32_e32 v41, v41, v52
	v_add_f32_e32 v41, v41, v53
	v_add_f32_e32 v41, v41, v54
	v_add_f32_e32 v41, v41, v55
	v_and_or_b32 v24, v41, s54, v81
	s_waitcnt lgkmcnt(2)
	v_add_f32_e32 v42, v42, v56
	v_add_f32_e32 v42, v42, v57
	v_add_f32_e32 v42, v42, v58
	v_add_f32_e32 v42, v42, v59
	v_and_or_b32 v21, v42, s54, v80
	s_waitcnt lgkmcnt(0)
	v_add_f32_e32 v43, v43, v60
	v_add_f32_e32 v43, v43, v61
	v_add_f32_e32 v43, v43, v62
	v_add_f32_e32 v43, v43, v63
	v_and_or_b32 v25, v43, s54, v81
	ds_read_b32 v44, v83 offset:4096
	ds_read_b128 v[64:67], v82 offset:4096
	ds_read_b32 v45, v83 offset:5120
	ds_read_b128 v[68:71], v82 offset:5120
	ds_read_b32 v46, v83 offset:6144
	ds_read_b128 v[72:75], v82 offset:6144
	ds_read_b32 v47, v83 offset:7168
	ds_read_b128 v[76:79], v82 offset:7168
	s_waitcnt lgkmcnt(6)
	v_add_f32_e32 v44, v44, v64
	v_add_f32_e32 v44, v44, v65
	v_add_f32_e32 v44, v44, v66
	v_add_f32_e32 v44, v44, v67
	v_and_or_b32 v22, v44, s54, v80
	s_waitcnt lgkmcnt(4)
	v_add_f32_e32 v45, v45, v68
	v_add_f32_e32 v45, v45, v69
	v_add_f32_e32 v45, v45, v70
	v_add_f32_e32 v45, v45, v71
	v_and_or_b32 v26, v45, s54, v81
	s_waitcnt lgkmcnt(2)
	v_add_f32_e32 v46, v46, v72
	v_add_f32_e32 v46, v46, v73
	v_add_f32_e32 v46, v46, v74
	v_add_f32_e32 v46, v46, v75
	v_and_or_b32 v23, v46, s54, v80
	s_waitcnt lgkmcnt(0)
	v_add_f32_e32 v47, v47, v76
	v_add_f32_e32 v47, v47, v77
	v_add_f32_e32 v47, v47, v78
	v_add_f32_e32 v47, v47, v79
	v_and_or_b32 v27, v47, s54, v81
	v_cmp_le_i32_e64 s[14:15], v184, s21
	v_cmp_lt_i32_e64 s[34:35], 0, v184
	s_nop 0
	s_and_b64 s[14:15], s[14:15], s[34:35]
	v_cmp_le_i32_e64 s[34:35], v84, s21
	v_cndmask_b32_e64 v20, 0, v20, s[14:15]
	s_nop 0
	v_cndmask_b32_e64 v24, 0, v24, s[34:35]
	v_mov_b32_e32 v36, 0
	v_cndmask_b32_e64 v21, 0, v21, s[14:15]
	v_cndmask_b32_e64 v25, 0, v25, s[34:35]
	v_mov_b32_e32 v37, 0
	v_cndmask_b32_e64 v22, 0, v22, s[14:15]
	v_cndmask_b32_e64 v26, 0, v26, s[34:35]
	v_mov_b32_e32 v38, 0
	v_cndmask_b32_e64 v23, 0, v23, s[14:15]
	v_cndmask_b32_e64 v27, 0, v27, s[34:35]
	v_mov_b32_e32 v39, 0
	v_max_u32_e32 v28, v20, v24
	v_max_u32_e32 v29, v21, v25
	v_max_u32_e32 v30, v22, v26
	v_max_u32_e32 v31, v23, v27
	v_max_u32_dpp v28, v28, v28 quad_perm:[1,0,3,2] row_mask:0xf bank_mask:0xf
	v_max_u32_dpp v29, v29, v29 quad_perm:[1,0,3,2] row_mask:0xf bank_mask:0xf
	v_max_u32_dpp v30, v30, v30 quad_perm:[1,0,3,2] row_mask:0xf bank_mask:0xf
	v_max_u32_dpp v31, v31, v31 quad_perm:[1,0,3,2] row_mask:0xf bank_mask:0xf
	v_max_u32_dpp v28, v28, v28 quad_perm:[2,3,0,1] row_mask:0xf bank_mask:0xf
	v_max_u32_dpp v29, v29, v29 quad_perm:[2,3,0,1] row_mask:0xf bank_mask:0xf
	v_max_u32_dpp v30, v30, v30 quad_perm:[2,3,0,1] row_mask:0xf bank_mask:0xf
	v_max_u32_dpp v31, v31, v31 quad_perm:[2,3,0,1] row_mask:0xf bank_mask:0xf
	v_max_u32_dpp v28, v28, v28 row_half_mirror row_mask:0xf bank_mask:0xf
	v_max_u32_dpp v29, v29, v29 row_half_mirror row_mask:0xf bank_mask:0xf
	v_max_u32_dpp v30, v30, v30 row_half_mirror row_mask:0xf bank_mask:0xf
	v_max_u32_dpp v31, v31, v31 row_half_mirror row_mask:0xf bank_mask:0xf
	v_max_u32_dpp v28, v28, v28 row_mirror row_mask:0xf bank_mask:0xf
	v_max_u32_dpp v29, v29, v29 row_mirror row_mask:0xf bank_mask:0xf
	v_max_u32_dpp v30, v30, v30 row_mirror row_mask:0xf bank_mask:0xf
	v_max_u32_dpp v31, v31, v31 row_mirror row_mask:0xf bank_mask:0xf
	ds_swizzle_b32 v32, v28 offset:0x401f
	ds_swizzle_b32 v33, v29 offset:0x401f
	ds_swizzle_b32 v34, v30 offset:0x401f
	ds_swizzle_b32 v35, v31 offset:0x401f
	s_waitcnt lgkmcnt(3)
	v_max_u32_e32 v28, v28, v32
	s_waitcnt lgkmcnt(2)
	v_max_u32_e32 v29, v29, v33
	s_waitcnt lgkmcnt(1)
	v_max_u32_e32 v30, v30, v34
	s_waitcnt lgkmcnt(0)
; __device__ __forceinline__ void nsa_quad_pre(int bg, int quad, const bf16_t* Q, const bf16_t* KV, const bf16_t* KCMP, const bf16_t* VCMPT, const float* GN, bf16_t* ONSA, ...
;     ...
;             for (int it = 0; it < 13; ++it) {
;                 unsigned m = k0 > k1 ? k0 : k1;
; #pragma unroll
;                 for (int off = 32; off >= 1; off >>= 1) { const unsigned o = (unsigned)__shfl_xor((int)m, off); m = o > m ? o : m; }
;                 if (k0 == m) k0 = 0u; if (k1 == m) k1 = 0u;
;                 if (lane == 0) selq[tt * 16 + it] = 127 - (int)(m & 127u);
	v_max_u32_e32 v31, v31, v35
	v_mov_b32_e32 v32, v28
	v_mov_b32_e32 v33, v29
	v_mov_b32_e32 v34, v30
	v_mov_b32_e32 v35, v31
	v_permlane32_swap_b32_e32 v28, v32
	v_permlane32_swap_b32_e32 v29, v33
	v_permlane32_swap_b32_e32 v30, v34
	v_permlane32_swap_b32_e32 v31, v35
	v_max_u32_e32 v28, v28, v32
	v_max_u32_e32 v29, v29, v33
	v_max_u32_e32 v30, v30, v34
	v_max_u32_e32 v31, v31, v35
	v_cmp_eq_u32_e64 s[0:1], 0, v184
	v_and_b32_e32 v84, 127, v28
	v_sub_u32_e32 v84, 127, v84
	v_and_b32_e32 v85, 127, v29
	v_sub_u32_e32 v85, 127, v85
	v_and_b32_e32 v86, 127, v30
	v_sub_u32_e32 v86, 127, v86
	v_and_b32_e32 v87, 127, v31
	v_sub_u32_e32 v87, 127, v87
	v_cndmask_b32_e64 v36, v36, v84, s[0:1]
	v_cndmask_b32_e64 v37, v37, v85, s[0:1]
	v_cndmask_b32_e64 v38, v38, v86, s[0:1]
	v_cndmask_b32_e64 v39, v39, v87, s[0:1]
	v_cmp_eq_u32_e64 s[14:15], v28, v20
	v_cmp_eq_u32_e64 s[34:35], v28, v24
	v_cmp_eq_u32_e64 s[42:43], v29, v21
	v_cmp_eq_u32_e64 s[66:67], v29, v25
	v_cndmask_b32_e64 v20, v20, 0, s[14:15]
	v_cndmask_b32_e64 v24, v24, 0, s[34:35]
	v_cndmask_b32_e64 v21, v21, 0, s[42:43]
	v_cndmask_b32_e64 v25, v25, 0, s[66:67]
	v_cmp_eq_u32_e64 s[14:15], v30, v22
	v_cmp_eq_u32_e64 s[34:35], v30, v26
	v_cmp_eq_u32_e64 s[42:43], v31, v23
	v_cmp_eq_u32_e64 s[66:67], v31, v27
	v_cndmask_b32_e64 v22, v22, 0, s[14:15]
	v_cndmask_b32_e64 v26, v26, 0, s[34:35]
	v_cndmask_b32_e64 v23, v23, 0, s[42:43]
	v_cndmask_b32_e64 v27, v27, 0, s[66:67]
	v_max_u32_e32 v28, v20, v24
	v_max_u32_e32 v29, v21, v25
	v_max_u32_e32 v30, v22, v26
	v_max_u32_e32 v31, v23, v27
	v_max_u32_dpp v28, v28, v28 quad_perm:[1,0,3,2] row_mask:0xf bank_mask:0xf
	v_max_u32_dpp v29, v29, v29 quad_perm:[1,0,3,2] row_mask:0xf bank_mask:0xf
	v_max_u32_dpp v30, v30, v30 quad_perm:[1,0,3,2] row_mask:0xf bank_mask:0xf
	v_max_u32_dpp v31, v31, v31 quad_perm:[1,0,3,2] row_mask:0xf bank_mask:0xf
	v_max_u32_dpp v28, v28, v28 quad_perm:[2,3,0,1] row_mask:0xf bank_mask:0xf
	v_max_u32_dpp v29, v29, v29 quad_perm:[2,3,0,1] row_mask:0xf bank_mask:0xf
	v_max_u32_dpp v30, v30, v30 quad_perm:[2,3,0,1] row_mask:0xf bank_mask:0xf
	v_max_u32_dpp v31, v31, v31 quad_perm:[2,3,0,1] row_mask:0xf bank_mask:0xf
	v_max_u32_dpp v28, v28, v28 row_half_mirror row_mask:0xf bank_mask:0xf
	v_max_u32_dpp v29, v29, v29 row_half_mirror row_mask:0xf bank_mask:0xf
	v_max_u32_dpp v30, v30, v30 row_half_mirror row_mask:0xf bank_mask:0xf
	v_max_u32_dpp v31, v31, v31 row_half_mirror row_mask:0xf bank_mask:0xf
	v_max_u32_dpp v28, v28, v28 row_mirror row_mask:0xf bank_mask:0xf
	v_max_u32_dpp v29, v29, v29 row_mirror row_mask:0xf bank_mask:0xf
	v_max_u32_dpp v30, v30, v30 row_mirror row_mask:0xf bank_mask:0xf
	v_max_u32_dpp v31, v31, v31 row_mirror row_mask:0xf bank_mask:0xf
	ds_swizzle_b32 v32, v28 offset:0x401f
	ds_swizzle_b32 v33, v29 offset:0x401f
	ds_swizzle_b32 v34, v30 offset:0x401f
	ds_swizzle_b32 v35, v31 offset:0x401f
	s_waitcnt lgkmcnt(3)
	v_max_u32_e32 v28, v28, v32
	s_waitcnt lgkmcnt(2)
	v_max_u32_e32 v29, v29, v33
	s_waitcnt lgkmcnt(1)
	v_max_u32_e32 v30, v30, v34
	s_waitcnt lgkmcnt(0)
	v_max_u32_e32 v31, v31, v35
	v_mov_b32_e32 v32, v28
	v_mov_b32_e32 v33, v29
	v_mov_b32_e32 v34, v30
	v_mov_b32_e32 v35, v31
	v_permlane32_swap_b32_e32 v28, v32
	v_permlane32_swap_b32_e32 v29, v33
	v_permlane32_swap_b32_e32 v30, v34
	v_permlane32_swap_b32_e32 v31, v35
	v_max_u32_e32 v28, v28, v32
	v_max_u32_e32 v29, v29, v33
	v_max_u32_e32 v30, v30, v34
	v_max_u32_e32 v31, v31, v35
	v_cmp_eq_u32_e64 s[0:1], 1, v184
	v_and_b32_e32 v84, 127, v28
	v_sub_u32_e32 v84, 127, v84
	v_and_b32_e32 v85, 127, v29
	v_sub_u32_e32 v85, 127, v85
	v_and_b32_e32 v86, 127, v30
	v_sub_u32_e32 v86, 127, v86
	v_and_b32_e32 v87, 127, v31
	v_sub_u32_e32 v87, 127, v87
	v_cndmask_b32_e64 v36, v36, v84, s[0:1]
	v_cndmask_b32_e64 v37, v37, v85, s[0:1]
	v_cndmask_b32_e64 v38, v38, v86, s[0:1]
	v_cndmask_b32_e64 v39, v39, v87, s[0:1]
	v_cmp_eq_u32_e64 s[14:15], v28, v20
	v_cmp_eq_u32_e64 s[34:35], v28, v24
	v_cmp_eq_u32_e64 s[42:43], v29, v21
	v_cmp_eq_u32_e64 s[66:67], v29, v25
	v_cndmask_b32_e64 v20, v20, 0, s[14:15]
	v_cndmask_b32_e64 v24, v24, 0, s[34:35]
	v_cndmask_b32_e64 v21, v21, 0, s[42:43]
	v_cndmask_b32_e64 v25, v25, 0, s[66:67]
	v_cmp_eq_u32_e64 s[14:15], v30, v22
	v_cmp_eq_u32_e64 s[34:35], v30, v26
	v_cmp_eq_u32_e64 s[42:43], v31, v23
	v_cmp_eq_u32_e64 s[66:67], v31, v27
	v_cndmask_b32_e64 v22, v22, 0, s[14:15]
	v_cndmask_b32_e64 v26, v26, 0, s[34:35]
	v_cndmask_b32_e64 v23, v23, 0, s[42:43]
	v_cndmask_b32_e64 v27, v27, 0, s[66:67]
	v_max_u32_e32 v28, v20, v24
	v_max_u32_e32 v29, v21, v25
	v_max_u32_e32 v30, v22, v26
	v_max_u32_e32 v31, v23, v27
	v_max_u32_dpp v28, v28, v28 quad_perm:[1,0,3,2] row_mask:0xf bank_mask:0xf
	v_max_u32_dpp v29, v29, v29 quad_perm:[1,0,3,2] row_mask:0xf bank_mask:0xf
	v_max_u32_dpp v30, v30, v30 quad_perm:[1,0,3,2] row_mask:0xf bank_mask:0xf
	v_max_u32_dpp v31, v31, v31 quad_perm:[1,0,3,2] row_mask:0xf bank_mask:0xf
	v_max_u32_dpp v28, v28, v28 quad_perm:[2,3,0,1] row_mask:0xf bank_mask:0xf
	v_max_u32_dpp v29, v29, v29 quad_perm:[2,3,0,1] row_mask:0xf bank_mask:0xf
	v_max_u32_dpp v30, v30, v30 quad_perm:[2,3,0,1] row_mask:0xf bank_mask:0xf
	v_max_u32_dpp v31, v31, v31 quad_perm:[2,3,0,1] row_mask:0xf bank_mask:0xf
	v_max_u32_dpp v28, v28, v28 row_half_mirror row_mask:0xf bank_mask:0xf
	v_max_u32_dpp v29, v29, v29 row_half_mirror row_mask:0xf bank_mask:0xf
	v_max_u32_dpp v30, v30, v30 row_half_mirror row_mask:0xf bank_mask:0xf
	v_max_u32_dpp v31, v31, v31 row_half_mirror row_mask:0xf bank_mask:0xf
	v_max_u32_dpp v28, v28, v28 row_mirror row_mask:0xf bank_mask:0xf
	v_max_u32_dpp v29, v29, v29 row_mirror row_mask:0xf bank_mask:0xf
	v_max_u32_dpp v30, v30, v30 row_mirror row_mask:0xf bank_mask:0xf
	v_max_u32_dpp v31, v31, v31 row_mirror row_mask:0xf bank_mask:0xf
	ds_swizzle_b32 v32, v28 offset:0x401f
	ds_swizzle_b32 v33, v29 offset:0x401f
	ds_swizzle_b32 v34, v30 offset:0x401f
	ds_swizzle_b32 v35, v31 offset:0x401f
	s_waitcnt lgkmcnt(3)
; __device__ __forceinline__ void nsa_quad_pre(int bg, int quad, const bf16_t* Q, const bf16_t* KV, const bf16_t* KCMP, const bf16_t* VCMPT, const float* GN, bf16_t* ONSA, ...
;     ...
;             for (int it = 0; it < 13; ++it) {
;                 unsigned m = k0 > k1 ? k0 : k1;
; #pragma unroll
;                 for (int off = 32; off >= 1; off >>= 1) { const unsigned o = (unsigned)__shfl_xor((int)m, off); m = o > m ? o : m; }
;                 if (k0 == m) k0 = 0u; if (k1 == m) k1 = 0u;
;                 if (lane == 0) selq[tt * 16 + it] = 127 - (int)(m & 127u);
	v_max_u32_e32 v28, v28, v32
	s_waitcnt lgkmcnt(2)
	v_max_u32_e32 v29, v29, v33
	s_waitcnt lgkmcnt(1)
	v_max_u32_e32 v30, v30, v34
	s_waitcnt lgkmcnt(0)
	v_max_u32_e32 v31, v31, v35
	v_mov_b32_e32 v32, v28
	v_mov_b32_e32 v33, v29
	v_mov_b32_e32 v34, v30
	v_mov_b32_e32 v35, v31
	v_permlane32_swap_b32_e32 v28, v32
	v_permlane32_swap_b32_e32 v29, v33
	v_permlane32_swap_b32_e32 v30, v34
	v_permlane32_swap_b32_e32 v31, v35
	v_max_u32_e32 v28, v28, v32
	v_max_u32_e32 v29, v29, v33
	v_max_u32_e32 v30, v30, v34
	v_max_u32_e32 v31, v31, v35
	v_cmp_eq_u32_e64 s[0:1], 2, v184
	v_and_b32_e32 v84, 127, v28
	v_sub_u32_e32 v84, 127, v84
	v_and_b32_e32 v85, 127, v29
	v_sub_u32_e32 v85, 127, v85
	v_and_b32_e32 v86, 127, v30
	v_sub_u32_e32 v86, 127, v86
	v_and_b32_e32 v87, 127, v31
	v_sub_u32_e32 v87, 127, v87
	v_cndmask_b32_e64 v36, v36, v84, s[0:1]
	v_cndmask_b32_e64 v37, v37, v85, s[0:1]
	v_cndmask_b32_e64 v38, v38, v86, s[0:1]
	v_cndmask_b32_e64 v39, v39, v87, s[0:1]
	v_cmp_eq_u32_e64 s[14:15], v28, v20
	v_cmp_eq_u32_e64 s[34:35], v28, v24
	v_cmp_eq_u32_e64 s[42:43], v29, v21
	v_cmp_eq_u32_e64 s[66:67], v29, v25
	v_cndmask_b32_e64 v20, v20, 0, s[14:15]
	v_cndmask_b32_e64 v24, v24, 0, s[34:35]
	v_cndmask_b32_e64 v21, v21, 0, s[42:43]
	v_cndmask_b32_e64 v25, v25, 0, s[66:67]
	v_cmp_eq_u32_e64 s[14:15], v30, v22
	v_cmp_eq_u32_e64 s[34:35], v30, v26
	v_cmp_eq_u32_e64 s[42:43], v31, v23
	v_cmp_eq_u32_e64 s[66:67], v31, v27
	v_cndmask_b32_e64 v22, v22, 0, s[14:15]
	v_cndmask_b32_e64 v26, v26, 0, s[34:35]
	v_cndmask_b32_e64 v23, v23, 0, s[42:43]
	v_cndmask_b32_e64 v27, v27, 0, s[66:67]
	v_max_u32_e32 v28, v20, v24
	v_max_u32_e32 v29, v21, v25
	v_max_u32_e32 v30, v22, v26
	v_max_u32_e32 v31, v23, v27
	v_max_u32_dpp v28, v28, v28 quad_perm:[1,0,3,2] row_mask:0xf bank_mask:0xf
	v_max_u32_dpp v29, v29, v29 quad_perm:[1,0,3,2] row_mask:0xf bank_mask:0xf
	v_max_u32_dpp v30, v30, v30 quad_perm:[1,0,3,2] row_mask:0xf bank_mask:0xf
	v_max_u32_dpp v31, v31, v31 quad_perm:[1,0,3,2] row_mask:0xf bank_mask:0xf
	v_max_u32_dpp v28, v28, v28 quad_perm:[2,3,0,1] row_mask:0xf bank_mask:0xf
	v_max_u32_dpp v29, v29, v29 quad_perm:[2,3,0,1] row_mask:0xf bank_mask:0xf
	v_max_u32_dpp v30, v30, v30 quad_perm:[2,3,0,1] row_mask:0xf bank_mask:0xf
	v_max_u32_dpp v31, v31, v31 quad_perm:[2,3,0,1] row_mask:0xf bank_mask:0xf
	v_max_u32_dpp v28, v28, v28 row_half_mirror row_mask:0xf bank_mask:0xf
	v_max_u32_dpp v29, v29, v29 row_half_mirror row_mask:0xf bank_mask:0xf
	v_max_u32_dpp v30, v30, v30 row_half_mirror row_mask:0xf bank_mask:0xf
	v_max_u32_dpp v31, v31, v31 row_half_mirror row_mask:0xf bank_mask:0xf
	v_max_u32_dpp v28, v28, v28 row_mirror row_mask:0xf bank_mask:0xf
	v_max_u32_dpp v29, v29, v29 row_mirror row_mask:0xf bank_mask:0xf
	v_max_u32_dpp v30, v30, v30 row_mirror row_mask:0xf bank_mask:0xf
	v_max_u32_dpp v31, v31, v31 row_mirror row_mask:0xf bank_mask:0xf
	ds_swizzle_b32 v32, v28 offset:0x401f
	ds_swizzle_b32 v33, v29 offset:0x401f
	ds_swizzle_b32 v34, v30 offset:0x401f
	ds_swizzle_b32 v35, v31 offset:0x401f
	s_waitcnt lgkmcnt(3)
	v_max_u32_e32 v28, v28, v32
	s_waitcnt lgkmcnt(2)
	v_max_u32_e32 v29, v29, v33
	s_waitcnt lgkmcnt(1)
	v_max_u32_e32 v30, v30, v34
	s_waitcnt lgkmcnt(0)
	v_max_u32_e32 v31, v31, v35
	v_mov_b32_e32 v32, v28
	v_mov_b32_e32 v33, v29
	v_mov_b32_e32 v34, v30
	v_mov_b32_e32 v35, v31
	v_permlane32_swap_b32_e32 v28, v32
	v_permlane32_swap_b32_e32 v29, v33
	v_permlane32_swap_b32_e32 v30, v34
	v_permlane32_swap_b32_e32 v31, v35
	v_max_u32_e32 v28, v28, v32
	v_max_u32_e32 v29, v29, v33
	v_max_u32_e32 v30, v30, v34
	v_max_u32_e32 v31, v31, v35
	v_cmp_eq_u32_e64 s[0:1], 3, v184
	v_and_b32_e32 v84, 127, v28
	v_sub_u32_e32 v84, 127, v84
	v_and_b32_e32 v85, 127, v29
	v_sub_u32_e32 v85, 127, v85
	v_and_b32_e32 v86, 127, v30
	v_sub_u32_e32 v86, 127, v86
	v_and_b32_e32 v87, 127, v31
	v_sub_u32_e32 v87, 127, v87
	v_cndmask_b32_e64 v36, v36, v84, s[0:1]
	v_cndmask_b32_e64 v37, v37, v85, s[0:1]
	v_cndmask_b32_e64 v38, v38, v86, s[0:1]
	v_cndmask_b32_e64 v39, v39, v87, s[0:1]
	v_cmp_eq_u32_e64 s[14:15], v28, v20
	v_cmp_eq_u32_e64 s[34:35], v28, v24
	v_cmp_eq_u32_e64 s[42:43], v29, v21
	v_cmp_eq_u32_e64 s[66:67], v29, v25
	v_cndmask_b32_e64 v20, v20, 0, s[14:15]
	v_cndmask_b32_e64 v24, v24, 0, s[34:35]
	v_cndmask_b32_e64 v21, v21, 0, s[42:43]
	v_cndmask_b32_e64 v25, v25, 0, s[66:67]
	v_cmp_eq_u32_e64 s[14:15], v30, v22
	v_cmp_eq_u32_e64 s[34:35], v30, v26
	v_cmp_eq_u32_e64 s[42:43], v31, v23
	v_cmp_eq_u32_e64 s[66:67], v31, v27
	v_cndmask_b32_e64 v22, v22, 0, s[14:15]
	v_cndmask_b32_e64 v26, v26, 0, s[34:35]
	v_cndmask_b32_e64 v23, v23, 0, s[42:43]
	v_cndmask_b32_e64 v27, v27, 0, s[66:67]
	v_max_u32_e32 v28, v20, v24
	v_max_u32_e32 v29, v21, v25
	v_max_u32_e32 v30, v22, v26
	v_max_u32_e32 v31, v23, v27
	v_max_u32_dpp v28, v28, v28 quad_perm:[1,0,3,2] row_mask:0xf bank_mask:0xf
	v_max_u32_dpp v29, v29, v29 quad_perm:[1,0,3,2] row_mask:0xf bank_mask:0xf
	v_max_u32_dpp v30, v30, v30 quad_perm:[1,0,3,2] row_mask:0xf bank_mask:0xf
	v_max_u32_dpp v31, v31, v31 quad_perm:[1,0,3,2] row_mask:0xf bank_mask:0xf
	v_max_u32_dpp v28, v28, v28 quad_perm:[2,3,0,1] row_mask:0xf bank_mask:0xf
	v_max_u32_dpp v29, v29, v29 quad_perm:[2,3,0,1] row_mask:0xf bank_mask:0xf
	v_max_u32_dpp v30, v30, v30 quad_perm:[2,3,0,1] row_mask:0xf bank_mask:0xf
	v_max_u32_dpp v31, v31, v31 quad_perm:[2,3,0,1] row_mask:0xf bank_mask:0xf
	v_max_u32_dpp v28, v28, v28 row_half_mirror row_mask:0xf bank_mask:0xf
	v_max_u32_dpp v29, v29, v29 row_half_mirror row_mask:0xf bank_mask:0xf
	v_max_u32_dpp v30, v30, v30 row_half_mirror row_mask:0xf bank_mask:0xf
	v_max_u32_dpp v31, v31, v31 row_half_mirror row_mask:0xf bank_mask:0xf
	v_max_u32_dpp v28, v28, v28 row_mirror row_mask:0xf bank_mask:0xf
	v_max_u32_dpp v29, v29, v29 row_mirror row_mask:0xf bank_mask:0xf
	v_max_u32_dpp v30, v30, v30 row_mirror row_mask:0xf bank_mask:0xf
	v_max_u32_dpp v31, v31, v31 row_mirror row_mask:0xf bank_mask:0xf
	ds_swizzle_b32 v32, v28 offset:0x401f
	ds_swizzle_b32 v33, v29 offset:0x401f
	ds_swizzle_b32 v34, v30 offset:0x401f
	ds_swizzle_b32 v35, v31 offset:0x401f
	s_waitcnt lgkmcnt(3)
; __device__ __forceinline__ void nsa_quad_pre(int bg, int quad, const bf16_t* Q, const bf16_t* KV, const bf16_t* KCMP, const bf16_t* VCMPT, const float* GN, bf16_t* ONSA, ...
;     ...
;             for (int it = 0; it < 13; ++it) {
;                 unsigned m = k0 > k1 ? k0 : k1;
; #pragma unroll
;                 for (int off = 32; off >= 1; off >>= 1) { const unsigned o = (unsigned)__shfl_xor((int)m, off); m = o > m ? o : m; }
;                 if (k0 == m) k0 = 0u; if (k1 == m) k1 = 0u;
;                 if (lane == 0) selq[tt * 16 + it] = 127 - (int)(m & 127u);
	v_max_u32_e32 v28, v28, v32
	s_waitcnt lgkmcnt(2)
	v_max_u32_e32 v29, v29, v33
	s_waitcnt lgkmcnt(1)
	v_max_u32_e32 v30, v30, v34
	s_waitcnt lgkmcnt(0)
	v_max_u32_e32 v31, v31, v35
	v_mov_b32_e32 v32, v28
	v_mov_b32_e32 v33, v29
	v_mov_b32_e32 v34, v30
	v_mov_b32_e32 v35, v31
	v_permlane32_swap_b32_e32 v28, v32
	v_permlane32_swap_b32_e32 v29, v33
	v_permlane32_swap_b32_e32 v30, v34
	v_permlane32_swap_b32_e32 v31, v35
	v_max_u32_e32 v28, v28, v32
	v_max_u32_e32 v29, v29, v33
	v_max_u32_e32 v30, v30, v34
	v_max_u32_e32 v31, v31, v35
	v_cmp_eq_u32_e64 s[0:1], 4, v184
	v_and_b32_e32 v84, 127, v28
	v_sub_u32_e32 v84, 127, v84
	v_and_b32_e32 v85, 127, v29
	v_sub_u32_e32 v85, 127, v85
	v_and_b32_e32 v86, 127, v30
	v_sub_u32_e32 v86, 127, v86
	v_and_b32_e32 v87, 127, v31
	v_sub_u32_e32 v87, 127, v87
	v_cndmask_b32_e64 v36, v36, v84, s[0:1]
	v_cndmask_b32_e64 v37, v37, v85, s[0:1]
	v_cndmask_b32_e64 v38, v38, v86, s[0:1]
	v_cndmask_b32_e64 v39, v39, v87, s[0:1]
	v_cmp_eq_u32_e64 s[14:15], v28, v20
	v_cmp_eq_u32_e64 s[34:35], v28, v24
	v_cmp_eq_u32_e64 s[42:43], v29, v21
	v_cmp_eq_u32_e64 s[66:67], v29, v25
	v_cndmask_b32_e64 v20, v20, 0, s[14:15]
	v_cndmask_b32_e64 v24, v24, 0, s[34:35]
	v_cndmask_b32_e64 v21, v21, 0, s[42:43]
	v_cndmask_b32_e64 v25, v25, 0, s[66:67]
	v_cmp_eq_u32_e64 s[14:15], v30, v22
	v_cmp_eq_u32_e64 s[34:35], v30, v26
	v_cmp_eq_u32_e64 s[42:43], v31, v23
	v_cmp_eq_u32_e64 s[66:67], v31, v27
	v_cndmask_b32_e64 v22, v22, 0, s[14:15]
	v_cndmask_b32_e64 v26, v26, 0, s[34:35]
	v_cndmask_b32_e64 v23, v23, 0, s[42:43]
	v_cndmask_b32_e64 v27, v27, 0, s[66:67]
	v_max_u32_e32 v28, v20, v24
	v_max_u32_e32 v29, v21, v25
	v_max_u32_e32 v30, v22, v26
	v_max_u32_e32 v31, v23, v27
	v_max_u32_dpp v28, v28, v28 quad_perm:[1,0,3,2] row_mask:0xf bank_mask:0xf
	v_max_u32_dpp v29, v29, v29 quad_perm:[1,0,3,2] row_mask:0xf bank_mask:0xf
	v_max_u32_dpp v30, v30, v30 quad_perm:[1,0,3,2] row_mask:0xf bank_mask:0xf
	v_max_u32_dpp v31, v31, v31 quad_perm:[1,0,3,2] row_mask:0xf bank_mask:0xf
	v_max_u32_dpp v28, v28, v28 quad_perm:[2,3,0,1] row_mask:0xf bank_mask:0xf
	v_max_u32_dpp v29, v29, v29 quad_perm:[2,3,0,1] row_mask:0xf bank_mask:0xf
	v_max_u32_dpp v30, v30, v30 quad_perm:[2,3,0,1] row_mask:0xf bank_mask:0xf
	v_max_u32_dpp v31, v31, v31 quad_perm:[2,3,0,1] row_mask:0xf bank_mask:0xf
	v_max_u32_dpp v28, v28, v28 row_half_mirror row_mask:0xf bank_mask:0xf
	v_max_u32_dpp v29, v29, v29 row_half_mirror row_mask:0xf bank_mask:0xf
	v_max_u32_dpp v30, v30, v30 row_half_mirror row_mask:0xf bank_mask:0xf
	v_max_u32_dpp v31, v31, v31 row_half_mirror row_mask:0xf bank_mask:0xf
	v_max_u32_dpp v28, v28, v28 row_mirror row_mask:0xf bank_mask:0xf
	v_max_u32_dpp v29, v29, v29 row_mirror row_mask:0xf bank_mask:0xf
	v_max_u32_dpp v30, v30, v30 row_mirror row_mask:0xf bank_mask:0xf
	v_max_u32_dpp v31, v31, v31 row_mirror row_mask:0xf bank_mask:0xf
	ds_swizzle_b32 v32, v28 offset:0x401f
	ds_swizzle_b32 v33, v29 offset:0x401f
	ds_swizzle_b32 v34, v30 offset:0x401f
	ds_swizzle_b32 v35, v31 offset:0x401f
	s_waitcnt lgkmcnt(3)
	v_max_u32_e32 v28, v28, v32
	s_waitcnt lgkmcnt(2)
	v_max_u32_e32 v29, v29, v33
	s_waitcnt lgkmcnt(1)
	v_max_u32_e32 v30, v30, v34
	s_waitcnt lgkmcnt(0)
	v_max_u32_e32 v31, v31, v35
	v_mov_b32_e32 v32, v28
	v_mov_b32_e32 v33, v29
	v_mov_b32_e32 v34, v30
	v_mov_b32_e32 v35, v31
	v_permlane32_swap_b32_e32 v28, v32
	v_permlane32_swap_b32_e32 v29, v33
	v_permlane32_swap_b32_e32 v30, v34
	v_permlane32_swap_b32_e32 v31, v35
	v_max_u32_e32 v28, v28, v32
	v_max_u32_e32 v29, v29, v33
	v_max_u32_e32 v30, v30, v34
	v_max_u32_e32 v31, v31, v35
	v_cmp_eq_u32_e64 s[0:1], 5, v184
	v_and_b32_e32 v84, 127, v28
	v_sub_u32_e32 v84, 127, v84
	v_and_b32_e32 v85, 127, v29
	v_sub_u32_e32 v85, 127, v85
	v_and_b32_e32 v86, 127, v30
	v_sub_u32_e32 v86, 127, v86
	v_and_b32_e32 v87, 127, v31
	v_sub_u32_e32 v87, 127, v87
	v_cndmask_b32_e64 v36, v36, v84, s[0:1]
	v_cndmask_b32_e64 v37, v37, v85, s[0:1]
	v_cndmask_b32_e64 v38, v38, v86, s[0:1]
	v_cndmask_b32_e64 v39, v39, v87, s[0:1]
	v_cmp_eq_u32_e64 s[14:15], v28, v20
	v_cmp_eq_u32_e64 s[34:35], v28, v24
	v_cmp_eq_u32_e64 s[42:43], v29, v21
	v_cmp_eq_u32_e64 s[66:67], v29, v25
	v_cndmask_b32_e64 v20, v20, 0, s[14:15]
	v_cndmask_b32_e64 v24, v24, 0, s[34:35]
	v_cndmask_b32_e64 v21, v21, 0, s[42:43]
	v_cndmask_b32_e64 v25, v25, 0, s[66:67]
	v_cmp_eq_u32_e64 s[14:15], v30, v22
	v_cmp_eq_u32_e64 s[34:35], v30, v26
	v_cmp_eq_u32_e64 s[42:43], v31, v23
	v_cmp_eq_u32_e64 s[66:67], v31, v27
	v_cndmask_b32_e64 v22, v22, 0, s[14:15]
	v_cndmask_b32_e64 v26, v26, 0, s[34:35]
	v_cndmask_b32_e64 v23, v23, 0, s[42:43]
	v_cndmask_b32_e64 v27, v27, 0, s[66:67]
	v_max_u32_e32 v28, v20, v24
	v_max_u32_e32 v29, v21, v25
	v_max_u32_e32 v30, v22, v26
	v_max_u32_e32 v31, v23, v27
	v_max_u32_dpp v28, v28, v28 quad_perm:[1,0,3,2] row_mask:0xf bank_mask:0xf
	v_max_u32_dpp v29, v29, v29 quad_perm:[1,0,3,2] row_mask:0xf bank_mask:0xf
	v_max_u32_dpp v30, v30, v30 quad_perm:[1,0,3,2] row_mask:0xf bank_mask:0xf
	v_max_u32_dpp v31, v31, v31 quad_perm:[1,0,3,2] row_mask:0xf bank_mask:0xf
	v_max_u32_dpp v28, v28, v28 quad_perm:[2,3,0,1] row_mask:0xf bank_mask:0xf
	v_max_u32_dpp v29, v29, v29 quad_perm:[2,3,0,1] row_mask:0xf bank_mask:0xf
	v_max_u32_dpp v30, v30, v30 quad_perm:[2,3,0,1] row_mask:0xf bank_mask:0xf
	v_max_u32_dpp v31, v31, v31 quad_perm:[2,3,0,1] row_mask:0xf bank_mask:0xf
	v_max_u32_dpp v28, v28, v28 row_half_mirror row_mask:0xf bank_mask:0xf
	v_max_u32_dpp v29, v29, v29 row_half_mirror row_mask:0xf bank_mask:0xf
	v_max_u32_dpp v30, v30, v30 row_half_mirror row_mask:0xf bank_mask:0xf
	v_max_u32_dpp v31, v31, v31 row_half_mirror row_mask:0xf bank_mask:0xf
	v_max_u32_dpp v28, v28, v28 row_mirror row_mask:0xf bank_mask:0xf
	v_max_u32_dpp v29, v29, v29 row_mirror row_mask:0xf bank_mask:0xf
	v_max_u32_dpp v30, v30, v30 row_mirror row_mask:0xf bank_mask:0xf
	v_max_u32_dpp v31, v31, v31 row_mirror row_mask:0xf bank_mask:0xf
	ds_swizzle_b32 v32, v28 offset:0x401f
	ds_swizzle_b32 v33, v29 offset:0x401f
	ds_swizzle_b32 v34, v30 offset:0x401f
	ds_swizzle_b32 v35, v31 offset:0x401f
	s_waitcnt lgkmcnt(3)
; __device__ __forceinline__ void nsa_quad_pre(int bg, int quad, const bf16_t* Q, const bf16_t* KV, const bf16_t* KCMP, const bf16_t* VCMPT, const float* GN, bf16_t* ONSA, ...
;     ...
;             for (int it = 0; it < 13; ++it) {
;                 unsigned m = k0 > k1 ? k0 : k1;
; #pragma unroll
;                 for (int off = 32; off >= 1; off >>= 1) { const unsigned o = (unsigned)__shfl_xor((int)m, off); m = o > m ? o : m; }
;                 if (k0 == m) k0 = 0u; if (k1 == m) k1 = 0u;
;                 if (lane == 0) selq[tt * 16 + it] = 127 - (int)(m & 127u);
	v_max_u32_e32 v28, v28, v32
	s_waitcnt lgkmcnt(2)
	v_max_u32_e32 v29, v29, v33
	s_waitcnt lgkmcnt(1)
	v_max_u32_e32 v30, v30, v34
	s_waitcnt lgkmcnt(0)
	v_max_u32_e32 v31, v31, v35
	v_mov_b32_e32 v32, v28
	v_mov_b32_e32 v33, v29
	v_mov_b32_e32 v34, v30
	v_mov_b32_e32 v35, v31
	v_permlane32_swap_b32_e32 v28, v32
	v_permlane32_swap_b32_e32 v29, v33
	v_permlane32_swap_b32_e32 v30, v34
	v_permlane32_swap_b32_e32 v31, v35
	v_max_u32_e32 v28, v28, v32
	v_max_u32_e32 v29, v29, v33
	v_max_u32_e32 v30, v30, v34
	v_max_u32_e32 v31, v31, v35
	v_cmp_eq_u32_e64 s[0:1], 6, v184
	v_and_b32_e32 v84, 127, v28
	v_sub_u32_e32 v84, 127, v84
	v_and_b32_e32 v85, 127, v29
	v_sub_u32_e32 v85, 127, v85
	v_and_b32_e32 v86, 127, v30
	v_sub_u32_e32 v86, 127, v86
	v_and_b32_e32 v87, 127, v31
	v_sub_u32_e32 v87, 127, v87
	v_cndmask_b32_e64 v36, v36, v84, s[0:1]
	v_cndmask_b32_e64 v37, v37, v85, s[0:1]
	v_cndmask_b32_e64 v38, v38, v86, s[0:1]
	v_cndmask_b32_e64 v39, v39, v87, s[0:1]
	v_cmp_eq_u32_e64 s[14:15], v28, v20
	v_cmp_eq_u32_e64 s[34:35], v28, v24
	v_cmp_eq_u32_e64 s[42:43], v29, v21
	v_cmp_eq_u32_e64 s[66:67], v29, v25
	v_cndmask_b32_e64 v20, v20, 0, s[14:15]
	v_cndmask_b32_e64 v24, v24, 0, s[34:35]
	v_cndmask_b32_e64 v21, v21, 0, s[42:43]
	v_cndmask_b32_e64 v25, v25, 0, s[66:67]
	v_cmp_eq_u32_e64 s[14:15], v30, v22
	v_cmp_eq_u32_e64 s[34:35], v30, v26
	v_cmp_eq_u32_e64 s[42:43], v31, v23
	v_cmp_eq_u32_e64 s[66:67], v31, v27
	v_cndmask_b32_e64 v22, v22, 0, s[14:15]
	v_cndmask_b32_e64 v26, v26, 0, s[34:35]
	v_cndmask_b32_e64 v23, v23, 0, s[42:43]
	v_cndmask_b32_e64 v27, v27, 0, s[66:67]
	v_max_u32_e32 v28, v20, v24
	v_max_u32_e32 v29, v21, v25
	v_max_u32_e32 v30, v22, v26
	v_max_u32_e32 v31, v23, v27
	v_max_u32_dpp v28, v28, v28 quad_perm:[1,0,3,2] row_mask:0xf bank_mask:0xf
	v_max_u32_dpp v29, v29, v29 quad_perm:[1,0,3,2] row_mask:0xf bank_mask:0xf
	v_max_u32_dpp v30, v30, v30 quad_perm:[1,0,3,2] row_mask:0xf bank_mask:0xf
	v_max_u32_dpp v31, v31, v31 quad_perm:[1,0,3,2] row_mask:0xf bank_mask:0xf
	v_max_u32_dpp v28, v28, v28 quad_perm:[2,3,0,1] row_mask:0xf bank_mask:0xf
	v_max_u32_dpp v29, v29, v29 quad_perm:[2,3,0,1] row_mask:0xf bank_mask:0xf
	v_max_u32_dpp v30, v30, v30 quad_perm:[2,3,0,1] row_mask:0xf bank_mask:0xf
	v_max_u32_dpp v31, v31, v31 quad_perm:[2,3,0,1] row_mask:0xf bank_mask:0xf
	v_max_u32_dpp v28, v28, v28 row_half_mirror row_mask:0xf bank_mask:0xf
	v_max_u32_dpp v29, v29, v29 row_half_mirror row_mask:0xf bank_mask:0xf
	v_max_u32_dpp v30, v30, v30 row_half_mirror row_mask:0xf bank_mask:0xf
	v_max_u32_dpp v31, v31, v31 row_half_mirror row_mask:0xf bank_mask:0xf
	v_max_u32_dpp v28, v28, v28 row_mirror row_mask:0xf bank_mask:0xf
	v_max_u32_dpp v29, v29, v29 row_mirror row_mask:0xf bank_mask:0xf
	v_max_u32_dpp v30, v30, v30 row_mirror row_mask:0xf bank_mask:0xf
	v_max_u32_dpp v31, v31, v31 row_mirror row_mask:0xf bank_mask:0xf
	ds_swizzle_b32 v32, v28 offset:0x401f
	ds_swizzle_b32 v33, v29 offset:0x401f
	ds_swizzle_b32 v34, v30 offset:0x401f
	ds_swizzle_b32 v35, v31 offset:0x401f
	s_waitcnt lgkmcnt(3)
	v_max_u32_e32 v28, v28, v32
	s_waitcnt lgkmcnt(2)
	v_max_u32_e32 v29, v29, v33
	s_waitcnt lgkmcnt(1)
	v_max_u32_e32 v30, v30, v34
	s_waitcnt lgkmcnt(0)
	v_max_u32_e32 v31, v31, v35
	v_mov_b32_e32 v32, v28
	v_mov_b32_e32 v33, v29
	v_mov_b32_e32 v34, v30
	v_mov_b32_e32 v35, v31
	v_permlane32_swap_b32_e32 v28, v32
	v_permlane32_swap_b32_e32 v29, v33
	v_permlane32_swap_b32_e32 v30, v34
	v_permlane32_swap_b32_e32 v31, v35
	v_max_u32_e32 v28, v28, v32
	v_max_u32_e32 v29, v29, v33
	v_max_u32_e32 v30, v30, v34
	v_max_u32_e32 v31, v31, v35
	v_cmp_eq_u32_e64 s[0:1], 7, v184
	v_and_b32_e32 v84, 127, v28
	v_sub_u32_e32 v84, 127, v84
	v_and_b32_e32 v85, 127, v29
	v_sub_u32_e32 v85, 127, v85
	v_and_b32_e32 v86, 127, v30
	v_sub_u32_e32 v86, 127, v86
	v_and_b32_e32 v87, 127, v31
	v_sub_u32_e32 v87, 127, v87
	v_cndmask_b32_e64 v36, v36, v84, s[0:1]
	v_cndmask_b32_e64 v37, v37, v85, s[0:1]
	v_cndmask_b32_e64 v38, v38, v86, s[0:1]
	v_cndmask_b32_e64 v39, v39, v87, s[0:1]
	v_cmp_eq_u32_e64 s[14:15], v28, v20
	v_cmp_eq_u32_e64 s[34:35], v28, v24
	v_cmp_eq_u32_e64 s[42:43], v29, v21
	v_cmp_eq_u32_e64 s[66:67], v29, v25
	v_cndmask_b32_e64 v20, v20, 0, s[14:15]
	v_cndmask_b32_e64 v24, v24, 0, s[34:35]
	v_cndmask_b32_e64 v21, v21, 0, s[42:43]
	v_cndmask_b32_e64 v25, v25, 0, s[66:67]
	v_cmp_eq_u32_e64 s[14:15], v30, v22
	v_cmp_eq_u32_e64 s[34:35], v30, v26
	v_cmp_eq_u32_e64 s[42:43], v31, v23
	v_cmp_eq_u32_e64 s[66:67], v31, v27
	v_cndmask_b32_e64 v22, v22, 0, s[14:15]
	v_cndmask_b32_e64 v26, v26, 0, s[34:35]
	v_cndmask_b32_e64 v23, v23, 0, s[42:43]
	v_cndmask_b32_e64 v27, v27, 0, s[66:67]
	v_max_u32_e32 v28, v20, v24
	v_max_u32_e32 v29, v21, v25
	v_max_u32_e32 v30, v22, v26
	v_max_u32_e32 v31, v23, v27
	v_max_u32_dpp v28, v28, v28 quad_perm:[1,0,3,2] row_mask:0xf bank_mask:0xf
	v_max_u32_dpp v29, v29, v29 quad_perm:[1,0,3,2] row_mask:0xf bank_mask:0xf
	v_max_u32_dpp v30, v30, v30 quad_perm:[1,0,3,2] row_mask:0xf bank_mask:0xf
	v_max_u32_dpp v31, v31, v31 quad_perm:[1,0,3,2] row_mask:0xf bank_mask:0xf
	v_max_u32_dpp v28, v28, v28 quad_perm:[2,3,0,1] row_mask:0xf bank_mask:0xf
	v_max_u32_dpp v29, v29, v29 quad_perm:[2,3,0,1] row_mask:0xf bank_mask:0xf
	v_max_u32_dpp v30, v30, v30 quad_perm:[2,3,0,1] row_mask:0xf bank_mask:0xf
	v_max_u32_dpp v31, v31, v31 quad_perm:[2,3,0,1] row_mask:0xf bank_mask:0xf
	v_max_u32_dpp v28, v28, v28 row_half_mirror row_mask:0xf bank_mask:0xf
	v_max_u32_dpp v29, v29, v29 row_half_mirror row_mask:0xf bank_mask:0xf
	v_max_u32_dpp v30, v30, v30 row_half_mirror row_mask:0xf bank_mask:0xf
	v_max_u32_dpp v31, v31, v31 row_half_mirror row_mask:0xf bank_mask:0xf
	v_max_u32_dpp v28, v28, v28 row_mirror row_mask:0xf bank_mask:0xf
	v_max_u32_dpp v29, v29, v29 row_mirror row_mask:0xf bank_mask:0xf
	v_max_u32_dpp v30, v30, v30 row_mirror row_mask:0xf bank_mask:0xf
	v_max_u32_dpp v31, v31, v31 row_mirror row_mask:0xf bank_mask:0xf
	ds_swizzle_b32 v32, v28 offset:0x401f
	ds_swizzle_b32 v33, v29 offset:0x401f
	ds_swizzle_b32 v34, v30 offset:0x401f
	ds_swizzle_b32 v35, v31 offset:0x401f
	s_waitcnt lgkmcnt(3)
; __device__ __forceinline__ void nsa_quad_pre(int bg, int quad, const bf16_t* Q, const bf16_t* KV, const bf16_t* KCMP, const bf16_t* VCMPT, const float* GN, bf16_t* ONSA, ...
;     ...
;             for (int it = 0; it < 13; ++it) {
;                 unsigned m = k0 > k1 ? k0 : k1;
; #pragma unroll
;                 for (int off = 32; off >= 1; off >>= 1) { const unsigned o = (unsigned)__shfl_xor((int)m, off); m = o > m ? o : m; }
;                 if (k0 == m) k0 = 0u; if (k1 == m) k1 = 0u;
;                 if (lane == 0) selq[tt * 16 + it] = 127 - (int)(m & 127u);
	v_max_u32_e32 v28, v28, v32
	s_waitcnt lgkmcnt(2)
	v_max_u32_e32 v29, v29, v33
	s_waitcnt lgkmcnt(1)
	v_max_u32_e32 v30, v30, v34
	s_waitcnt lgkmcnt(0)
	v_max_u32_e32 v31, v31, v35
	v_mov_b32_e32 v32, v28
	v_mov_b32_e32 v33, v29
	v_mov_b32_e32 v34, v30
	v_mov_b32_e32 v35, v31
	v_permlane32_swap_b32_e32 v28, v32
	v_permlane32_swap_b32_e32 v29, v33
	v_permlane32_swap_b32_e32 v30, v34
	v_permlane32_swap_b32_e32 v31, v35
	v_max_u32_e32 v28, v28, v32
	v_max_u32_e32 v29, v29, v33
	v_max_u32_e32 v30, v30, v34
	v_max_u32_e32 v31, v31, v35
	v_cmp_eq_u32_e64 s[0:1], 8, v184
	v_and_b32_e32 v84, 127, v28
	v_sub_u32_e32 v84, 127, v84
	v_and_b32_e32 v85, 127, v29
	v_sub_u32_e32 v85, 127, v85
	v_and_b32_e32 v86, 127, v30
	v_sub_u32_e32 v86, 127, v86
	v_and_b32_e32 v87, 127, v31
	v_sub_u32_e32 v87, 127, v87
	v_cndmask_b32_e64 v36, v36, v84, s[0:1]
	v_cndmask_b32_e64 v37, v37, v85, s[0:1]
	v_cndmask_b32_e64 v38, v38, v86, s[0:1]
	v_cndmask_b32_e64 v39, v39, v87, s[0:1]
	v_cmp_eq_u32_e64 s[14:15], v28, v20
	v_cmp_eq_u32_e64 s[34:35], v28, v24
	v_cmp_eq_u32_e64 s[42:43], v29, v21
	v_cmp_eq_u32_e64 s[66:67], v29, v25
	v_cndmask_b32_e64 v20, v20, 0, s[14:15]
	v_cndmask_b32_e64 v24, v24, 0, s[34:35]
	v_cndmask_b32_e64 v21, v21, 0, s[42:43]
	v_cndmask_b32_e64 v25, v25, 0, s[66:67]
	v_cmp_eq_u32_e64 s[14:15], v30, v22
	v_cmp_eq_u32_e64 s[34:35], v30, v26
	v_cmp_eq_u32_e64 s[42:43], v31, v23
	v_cmp_eq_u32_e64 s[66:67], v31, v27
	v_cndmask_b32_e64 v22, v22, 0, s[14:15]
	v_cndmask_b32_e64 v26, v26, 0, s[34:35]
	v_cndmask_b32_e64 v23, v23, 0, s[42:43]
	v_cndmask_b32_e64 v27, v27, 0, s[66:67]
	v_max_u32_e32 v28, v20, v24
	v_max_u32_e32 v29, v21, v25
	v_max_u32_e32 v30, v22, v26
	v_max_u32_e32 v31, v23, v27
	v_max_u32_dpp v28, v28, v28 quad_perm:[1,0,3,2] row_mask:0xf bank_mask:0xf
	v_max_u32_dpp v29, v29, v29 quad_perm:[1,0,3,2] row_mask:0xf bank_mask:0xf
	v_max_u32_dpp v30, v30, v30 quad_perm:[1,0,3,2] row_mask:0xf bank_mask:0xf
	v_max_u32_dpp v31, v31, v31 quad_perm:[1,0,3,2] row_mask:0xf bank_mask:0xf
	v_max_u32_dpp v28, v28, v28 quad_perm:[2,3,0,1] row_mask:0xf bank_mask:0xf
	v_max_u32_dpp v29, v29, v29 quad_perm:[2,3,0,1] row_mask:0xf bank_mask:0xf
	v_max_u32_dpp v30, v30, v30 quad_perm:[2,3,0,1] row_mask:0xf bank_mask:0xf
	v_max_u32_dpp v31, v31, v31 quad_perm:[2,3,0,1] row_mask:0xf bank_mask:0xf
	v_max_u32_dpp v28, v28, v28 row_half_mirror row_mask:0xf bank_mask:0xf
	v_max_u32_dpp v29, v29, v29 row_half_mirror row_mask:0xf bank_mask:0xf
	v_max_u32_dpp v30, v30, v30 row_half_mirror row_mask:0xf bank_mask:0xf
	v_max_u32_dpp v31, v31, v31 row_half_mirror row_mask:0xf bank_mask:0xf
	v_max_u32_dpp v28, v28, v28 row_mirror row_mask:0xf bank_mask:0xf
	v_max_u32_dpp v29, v29, v29 row_mirror row_mask:0xf bank_mask:0xf
	v_max_u32_dpp v30, v30, v30 row_mirror row_mask:0xf bank_mask:0xf
	v_max_u32_dpp v31, v31, v31 row_mirror row_mask:0xf bank_mask:0xf
	ds_swizzle_b32 v32, v28 offset:0x401f
	ds_swizzle_b32 v33, v29 offset:0x401f
	ds_swizzle_b32 v34, v30 offset:0x401f
	ds_swizzle_b32 v35, v31 offset:0x401f
	s_waitcnt lgkmcnt(3)
	v_max_u32_e32 v28, v28, v32
	s_waitcnt lgkmcnt(2)
	v_max_u32_e32 v29, v29, v33
	s_waitcnt lgkmcnt(1)
	v_max_u32_e32 v30, v30, v34
	s_waitcnt lgkmcnt(0)
	v_max_u32_e32 v31, v31, v35
	v_mov_b32_e32 v32, v28
	v_mov_b32_e32 v33, v29
	v_mov_b32_e32 v34, v30
	v_mov_b32_e32 v35, v31
	v_permlane32_swap_b32_e32 v28, v32
	v_permlane32_swap_b32_e32 v29, v33
	v_permlane32_swap_b32_e32 v30, v34
	v_permlane32_swap_b32_e32 v31, v35
	v_max_u32_e32 v28, v28, v32
	v_max_u32_e32 v29, v29, v33
	v_max_u32_e32 v30, v30, v34
	v_max_u32_e32 v31, v31, v35
	v_cmp_eq_u32_e64 s[0:1], 9, v184
	v_and_b32_e32 v84, 127, v28
	v_sub_u32_e32 v84, 127, v84
	v_and_b32_e32 v85, 127, v29
	v_sub_u32_e32 v85, 127, v85
	v_and_b32_e32 v86, 127, v30
	v_sub_u32_e32 v86, 127, v86
	v_and_b32_e32 v87, 127, v31
	v_sub_u32_e32 v87, 127, v87
	v_cndmask_b32_e64 v36, v36, v84, s[0:1]
	v_cndmask_b32_e64 v37, v37, v85, s[0:1]
	v_cndmask_b32_e64 v38, v38, v86, s[0:1]
	v_cndmask_b32_e64 v39, v39, v87, s[0:1]
	v_cmp_eq_u32_e64 s[14:15], v28, v20
	v_cmp_eq_u32_e64 s[34:35], v28, v24
	v_cmp_eq_u32_e64 s[42:43], v29, v21
	v_cmp_eq_u32_e64 s[66:67], v29, v25
	v_cndmask_b32_e64 v20, v20, 0, s[14:15]
	v_cndmask_b32_e64 v24, v24, 0, s[34:35]
	v_cndmask_b32_e64 v21, v21, 0, s[42:43]
	v_cndmask_b32_e64 v25, v25, 0, s[66:67]
	v_cmp_eq_u32_e64 s[14:15], v30, v22
	v_cmp_eq_u32_e64 s[34:35], v30, v26
	v_cmp_eq_u32_e64 s[42:43], v31, v23
	v_cmp_eq_u32_e64 s[66:67], v31, v27
	v_cndmask_b32_e64 v22, v22, 0, s[14:15]
	v_cndmask_b32_e64 v26, v26, 0, s[34:35]
	v_cndmask_b32_e64 v23, v23, 0, s[42:43]
	v_cndmask_b32_e64 v27, v27, 0, s[66:67]
	v_max_u32_e32 v28, v20, v24
	v_max_u32_e32 v29, v21, v25
	v_max_u32_e32 v30, v22, v26
	v_max_u32_e32 v31, v23, v27
	v_max_u32_dpp v28, v28, v28 quad_perm:[1,0,3,2] row_mask:0xf bank_mask:0xf
	v_max_u32_dpp v29, v29, v29 quad_perm:[1,0,3,2] row_mask:0xf bank_mask:0xf
	v_max_u32_dpp v30, v30, v30 quad_perm:[1,0,3,2] row_mask:0xf bank_mask:0xf
	v_max_u32_dpp v31, v31, v31 quad_perm:[1,0,3,2] row_mask:0xf bank_mask:0xf
	v_max_u32_dpp v28, v28, v28 quad_perm:[2,3,0,1] row_mask:0xf bank_mask:0xf
	v_max_u32_dpp v29, v29, v29 quad_perm:[2,3,0,1] row_mask:0xf bank_mask:0xf
	v_max_u32_dpp v30, v30, v30 quad_perm:[2,3,0,1] row_mask:0xf bank_mask:0xf
	v_max_u32_dpp v31, v31, v31 quad_perm:[2,3,0,1] row_mask:0xf bank_mask:0xf
	v_max_u32_dpp v28, v28, v28 row_half_mirror row_mask:0xf bank_mask:0xf
	v_max_u32_dpp v29, v29, v29 row_half_mirror row_mask:0xf bank_mask:0xf
	v_max_u32_dpp v30, v30, v30 row_half_mirror row_mask:0xf bank_mask:0xf
	v_max_u32_dpp v31, v31, v31 row_half_mirror row_mask:0xf bank_mask:0xf
	v_max_u32_dpp v28, v28, v28 row_mirror row_mask:0xf bank_mask:0xf
	v_max_u32_dpp v29, v29, v29 row_mirror row_mask:0xf bank_mask:0xf
	v_max_u32_dpp v30, v30, v30 row_mirror row_mask:0xf bank_mask:0xf
	v_max_u32_dpp v31, v31, v31 row_mirror row_mask:0xf bank_mask:0xf
	ds_swizzle_b32 v32, v28 offset:0x401f
	ds_swizzle_b32 v33, v29 offset:0x401f
	ds_swizzle_b32 v34, v30 offset:0x401f
	ds_swizzle_b32 v35, v31 offset:0x401f
	s_waitcnt lgkmcnt(3)
; __device__ __forceinline__ void nsa_quad_pre(int bg, int quad, const bf16_t* Q, const bf16_t* KV, const bf16_t* KCMP, const bf16_t* VCMPT, const float* GN, bf16_t* ONSA, ...
;     ...
;             for (int it = 0; it < 13; ++it) {
;                 unsigned m = k0 > k1 ? k0 : k1;
; #pragma unroll
;                 for (int off = 32; off >= 1; off >>= 1) { const unsigned o = (unsigned)__shfl_xor((int)m, off); m = o > m ? o : m; }
;                 if (k0 == m) k0 = 0u; if (k1 == m) k1 = 0u;
;                 if (lane == 0) selq[tt * 16 + it] = 127 - (int)(m & 127u);
	v_max_u32_e32 v28, v28, v32
	s_waitcnt lgkmcnt(2)
	v_max_u32_e32 v29, v29, v33
	s_waitcnt lgkmcnt(1)
	v_max_u32_e32 v30, v30, v34
	s_waitcnt lgkmcnt(0)
	v_max_u32_e32 v31, v31, v35
	v_mov_b32_e32 v32, v28
	v_mov_b32_e32 v33, v29
	v_mov_b32_e32 v34, v30
	v_mov_b32_e32 v35, v31
	v_permlane32_swap_b32_e32 v28, v32
	v_permlane32_swap_b32_e32 v29, v33
	v_permlane32_swap_b32_e32 v30, v34
	v_permlane32_swap_b32_e32 v31, v35
	v_max_u32_e32 v28, v28, v32
	v_max_u32_e32 v29, v29, v33
	v_max_u32_e32 v30, v30, v34
	v_max_u32_e32 v31, v31, v35
	v_cmp_eq_u32_e64 s[0:1], 10, v184
	v_and_b32_e32 v84, 127, v28
	v_sub_u32_e32 v84, 127, v84
	v_and_b32_e32 v85, 127, v29
	v_sub_u32_e32 v85, 127, v85
	v_and_b32_e32 v86, 127, v30
	v_sub_u32_e32 v86, 127, v86
	v_and_b32_e32 v87, 127, v31
	v_sub_u32_e32 v87, 127, v87
	v_cndmask_b32_e64 v36, v36, v84, s[0:1]
	v_cndmask_b32_e64 v37, v37, v85, s[0:1]
	v_cndmask_b32_e64 v38, v38, v86, s[0:1]
	v_cndmask_b32_e64 v39, v39, v87, s[0:1]
	v_cmp_eq_u32_e64 s[14:15], v28, v20
	v_cmp_eq_u32_e64 s[34:35], v28, v24
	v_cmp_eq_u32_e64 s[42:43], v29, v21
	v_cmp_eq_u32_e64 s[66:67], v29, v25
	v_cndmask_b32_e64 v20, v20, 0, s[14:15]
	v_cndmask_b32_e64 v24, v24, 0, s[34:35]
	v_cndmask_b32_e64 v21, v21, 0, s[42:43]
	v_cndmask_b32_e64 v25, v25, 0, s[66:67]
	v_cmp_eq_u32_e64 s[14:15], v30, v22
	v_cmp_eq_u32_e64 s[34:35], v30, v26
	v_cmp_eq_u32_e64 s[42:43], v31, v23
	v_cmp_eq_u32_e64 s[66:67], v31, v27
	v_cndmask_b32_e64 v22, v22, 0, s[14:15]
	v_cndmask_b32_e64 v26, v26, 0, s[34:35]
	v_cndmask_b32_e64 v23, v23, 0, s[42:43]
	v_cndmask_b32_e64 v27, v27, 0, s[66:67]
	v_max_u32_e32 v28, v20, v24
	v_max_u32_e32 v29, v21, v25
	v_max_u32_e32 v30, v22, v26
	v_max_u32_e32 v31, v23, v27
	v_max_u32_dpp v28, v28, v28 quad_perm:[1,0,3,2] row_mask:0xf bank_mask:0xf
	v_max_u32_dpp v29, v29, v29 quad_perm:[1,0,3,2] row_mask:0xf bank_mask:0xf
	v_max_u32_dpp v30, v30, v30 quad_perm:[1,0,3,2] row_mask:0xf bank_mask:0xf
	v_max_u32_dpp v31, v31, v31 quad_perm:[1,0,3,2] row_mask:0xf bank_mask:0xf
	v_max_u32_dpp v28, v28, v28 quad_perm:[2,3,0,1] row_mask:0xf bank_mask:0xf
	v_max_u32_dpp v29, v29, v29 quad_perm:[2,3,0,1] row_mask:0xf bank_mask:0xf
	v_max_u32_dpp v30, v30, v30 quad_perm:[2,3,0,1] row_mask:0xf bank_mask:0xf
	v_max_u32_dpp v31, v31, v31 quad_perm:[2,3,0,1] row_mask:0xf bank_mask:0xf
	v_max_u32_dpp v28, v28, v28 row_half_mirror row_mask:0xf bank_mask:0xf
	v_max_u32_dpp v29, v29, v29 row_half_mirror row_mask:0xf bank_mask:0xf
	v_max_u32_dpp v30, v30, v30 row_half_mirror row_mask:0xf bank_mask:0xf
	v_max_u32_dpp v31, v31, v31 row_half_mirror row_mask:0xf bank_mask:0xf
	v_max_u32_dpp v28, v28, v28 row_mirror row_mask:0xf bank_mask:0xf
	v_max_u32_dpp v29, v29, v29 row_mirror row_mask:0xf bank_mask:0xf
	v_max_u32_dpp v30, v30, v30 row_mirror row_mask:0xf bank_mask:0xf
	v_max_u32_dpp v31, v31, v31 row_mirror row_mask:0xf bank_mask:0xf
	ds_swizzle_b32 v32, v28 offset:0x401f
	ds_swizzle_b32 v33, v29 offset:0x401f
	ds_swizzle_b32 v34, v30 offset:0x401f
	ds_swizzle_b32 v35, v31 offset:0x401f
	s_waitcnt lgkmcnt(3)
	v_max_u32_e32 v28, v28, v32
	s_waitcnt lgkmcnt(2)
	v_max_u32_e32 v29, v29, v33
	s_waitcnt lgkmcnt(1)
	v_max_u32_e32 v30, v30, v34
	s_waitcnt lgkmcnt(0)
; __device__ __forceinline__ void nsa_quad_pre(int bg, int quad, const bf16_t* Q, const bf16_t* KV, const bf16_t* KCMP, const bf16_t* VCMPT, const float* GN, bf16_t* ONSA, ...
;     ...
;             for (int it = 0; it < 13; ++it) {
;                 unsigned m = k0 > k1 ? k0 : k1;
; #pragma unroll
;                 for (int off = 32; off >= 1; off >>= 1) { const unsigned o = (unsigned)__shfl_xor((int)m, off); m = o > m ? o : m; }
;                 if (k0 == m) k0 = 0u; if (k1 == m) k1 = 0u;
;                 if (lane == 0) selq[tt * 16 + it] = 127 - (int)(m & 127u);
;             }
;             if (lane == 0) { selq[tt * 16 + 13] = 0; selq[tt * 16 + 14] = cur - 1; selq[tt * 16 + 15] = cur; }
	v_max_u32_e32 v31, v31, v35
	v_mov_b32_e32 v32, v28
	v_mov_b32_e32 v33, v29
	v_mov_b32_e32 v34, v30
	v_mov_b32_e32 v35, v31
	v_permlane32_swap_b32_e32 v28, v32
	v_permlane32_swap_b32_e32 v29, v33
	v_permlane32_swap_b32_e32 v30, v34
	v_permlane32_swap_b32_e32 v31, v35
	v_max_u32_e32 v28, v28, v32
	v_max_u32_e32 v29, v29, v33
	v_max_u32_e32 v30, v30, v34
	v_max_u32_e32 v31, v31, v35
	v_cmp_eq_u32_e64 s[0:1], 11, v184
	v_and_b32_e32 v84, 127, v28
	v_sub_u32_e32 v84, 127, v84
	v_and_b32_e32 v85, 127, v29
	v_sub_u32_e32 v85, 127, v85
	v_and_b32_e32 v86, 127, v30
	v_sub_u32_e32 v86, 127, v86
	v_and_b32_e32 v87, 127, v31
	v_sub_u32_e32 v87, 127, v87
	v_cndmask_b32_e64 v36, v36, v84, s[0:1]
	v_cndmask_b32_e64 v37, v37, v85, s[0:1]
	v_cndmask_b32_e64 v38, v38, v86, s[0:1]
	v_cndmask_b32_e64 v39, v39, v87, s[0:1]
	v_cmp_eq_u32_e64 s[14:15], v28, v20
	v_cmp_eq_u32_e64 s[34:35], v28, v24
	v_cmp_eq_u32_e64 s[42:43], v29, v21
	v_cmp_eq_u32_e64 s[66:67], v29, v25
	v_cndmask_b32_e64 v20, v20, 0, s[14:15]
	v_cndmask_b32_e64 v24, v24, 0, s[34:35]
	v_cndmask_b32_e64 v21, v21, 0, s[42:43]
	v_cndmask_b32_e64 v25, v25, 0, s[66:67]
	v_cmp_eq_u32_e64 s[14:15], v30, v22
	v_cmp_eq_u32_e64 s[34:35], v30, v26
	v_cmp_eq_u32_e64 s[42:43], v31, v23
	v_cmp_eq_u32_e64 s[66:67], v31, v27
	v_cndmask_b32_e64 v22, v22, 0, s[14:15]
	v_cndmask_b32_e64 v26, v26, 0, s[34:35]
	v_cndmask_b32_e64 v23, v23, 0, s[42:43]
	v_cndmask_b32_e64 v27, v27, 0, s[66:67]
	v_max_u32_e32 v28, v20, v24
	v_max_u32_e32 v29, v21, v25
	v_max_u32_e32 v30, v22, v26
	v_max_u32_e32 v31, v23, v27
	v_max_u32_dpp v28, v28, v28 quad_perm:[1,0,3,2] row_mask:0xf bank_mask:0xf
	v_max_u32_dpp v29, v29, v29 quad_perm:[1,0,3,2] row_mask:0xf bank_mask:0xf
	v_max_u32_dpp v30, v30, v30 quad_perm:[1,0,3,2] row_mask:0xf bank_mask:0xf
	v_max_u32_dpp v31, v31, v31 quad_perm:[1,0,3,2] row_mask:0xf bank_mask:0xf
	v_max_u32_dpp v28, v28, v28 quad_perm:[2,3,0,1] row_mask:0xf bank_mask:0xf
	v_max_u32_dpp v29, v29, v29 quad_perm:[2,3,0,1] row_mask:0xf bank_mask:0xf
	v_max_u32_dpp v30, v30, v30 quad_perm:[2,3,0,1] row_mask:0xf bank_mask:0xf
	v_max_u32_dpp v31, v31, v31 quad_perm:[2,3,0,1] row_mask:0xf bank_mask:0xf
	v_max_u32_dpp v28, v28, v28 row_half_mirror row_mask:0xf bank_mask:0xf
	v_max_u32_dpp v29, v29, v29 row_half_mirror row_mask:0xf bank_mask:0xf
	v_max_u32_dpp v30, v30, v30 row_half_mirror row_mask:0xf bank_mask:0xf
	v_max_u32_dpp v31, v31, v31 row_half_mirror row_mask:0xf bank_mask:0xf
	v_max_u32_dpp v28, v28, v28 row_mirror row_mask:0xf bank_mask:0xf
	v_max_u32_dpp v29, v29, v29 row_mirror row_mask:0xf bank_mask:0xf
	v_max_u32_dpp v30, v30, v30 row_mirror row_mask:0xf bank_mask:0xf
	v_max_u32_dpp v31, v31, v31 row_mirror row_mask:0xf bank_mask:0xf
	ds_swizzle_b32 v32, v28 offset:0x401f
	ds_swizzle_b32 v33, v29 offset:0x401f
	ds_swizzle_b32 v34, v30 offset:0x401f
	ds_swizzle_b32 v35, v31 offset:0x401f
	s_waitcnt lgkmcnt(3)
	v_max_u32_e32 v28, v28, v32
	s_waitcnt lgkmcnt(2)
	v_max_u32_e32 v29, v29, v33
	s_waitcnt lgkmcnt(1)
	v_max_u32_e32 v30, v30, v34
	s_waitcnt lgkmcnt(0)
	v_max_u32_e32 v31, v31, v35
	v_mov_b32_e32 v32, v28
	v_mov_b32_e32 v33, v29
	v_mov_b32_e32 v34, v30
	v_mov_b32_e32 v35, v31
	v_permlane32_swap_b32_e32 v28, v32
	v_permlane32_swap_b32_e32 v29, v33
	v_permlane32_swap_b32_e32 v30, v34
	v_permlane32_swap_b32_e32 v31, v35
	v_max_u32_e32 v28, v28, v32
	v_max_u32_e32 v29, v29, v33
	v_max_u32_e32 v30, v30, v34
	v_max_u32_e32 v31, v31, v35
	v_cmp_eq_u32_e64 s[0:1], 12, v184
	v_and_b32_e32 v84, 127, v28
	v_sub_u32_e32 v84, 127, v84
	v_and_b32_e32 v85, 127, v29
	v_sub_u32_e32 v85, 127, v85
	v_and_b32_e32 v86, 127, v30
	v_sub_u32_e32 v86, 127, v86
	v_and_b32_e32 v87, 127, v31
	v_sub_u32_e32 v87, 127, v87
	v_cndmask_b32_e64 v36, v36, v84, s[0:1]
	v_cndmask_b32_e64 v37, v37, v85, s[0:1]
	v_cndmask_b32_e64 v38, v38, v86, s[0:1]
	v_cndmask_b32_e64 v39, v39, v87, s[0:1]
	s_add_i32 s19, s18, -1
	v_mov_b32_e32 v84, s19
	v_mov_b32_e32 v85, s18
	v_cmp_eq_u32_e64 s[14:15], 14, v184
	v_cmp_eq_u32_e64 s[34:35], 15, v184
	s_nop 0
	v_cndmask_b32_e64 v36, v36, v84, s[14:15]
	v_cndmask_b32_e64 v36, v36, v85, s[34:35]
	v_cndmask_b32_e64 v37, v37, v84, s[14:15]
	v_cndmask_b32_e64 v37, v37, v85, s[34:35]
	v_cndmask_b32_e64 v38, v38, v84, s[14:15]
	v_cndmask_b32_e64 v38, v38, v85, s[34:35]
	v_cndmask_b32_e64 v39, v39, v84, s[14:15]
	v_cndmask_b32_e64 v39, v39, v85, s[34:35]
	s_and_saveexec_b64 s[42:43], s[6:7]
	ds_write_b32 v196, v36 offset:51264
	ds_write_b32 v196, v37 offset:51328
	ds_write_b32 v196, v38 offset:51392
	ds_write_b32 v196, v39 offset:51456
	s_or_b64 exec, exec, s[42:43]
	s_branch .Ltopk_done_q0
.Ltopk_small_q0:
	s_nop 1
	s_and_saveexec_b64 s[42:43], s[6:7]
	ds_write_b32 v196, v184 offset:51264
	ds_write_b32 v196, v184 offset:51328
	ds_write_b32 v196, v184 offset:51392
	ds_write_b32 v196, v184 offset:51456
	s_or_b64 exec, exec, s[42:43]
.Ltopk_done_q0:
	s_nop 0
	s_waitcnt lgkmcnt(0)

; #define LAS __attribute__((address_space(3)))
; __device__ __forceinline__ void nsa_quad_pre(int bg, int quad, const bf16_t* Q, const bf16_t* KV, const bf16_t* KCMP, const bf16_t* VCMPT, const float* GN, bf16_t* ONSA, ...
;     ...
; #pragma unroll
;     for (int tt = 0; tt < 4; ++tt) {
;         const int tok = t0 + tt, cur = tok >> 6;
;         if (cur < 16) { if (lane < 16) selq[tt * 16 + lane] = lane; }
;         else {
;             unsigned k0 = 0u, k1 = 0u;
;             { const int j = lane; if (j >= 1 && j <= cur - 2) { const LAS float* ps = psum + tt * 512 + 4 * j - 1; const float v = ps[0] + ps[1] + ps[2] + ps[3] + ps[4]; k0 = (__builtin_bit_cast(unsigned, v) & ~127u) | (unsigned)(127 - j); } }
;             { const int j = lane + 64; if (j <= cur - 2) { const LAS float* ps = psum + tt * 512 + 4 * j - 1; const float v = ps[0] + ps[1] + ps[2] + ps[3] + ps[4]; k1 = (__builtin_bit_cast(unsigned, v) & ~127u) | (unsigned)(127 - j); } }
;             for (int it = 0; it < 13; ++it) {
;                 unsigned m = k0 > k1 ? k0 : k1;
; #pragma unroll
;                 for (int off = 32; off >= 1; off >>= 1) { const unsigned o = (unsigned)__shfl_xor((int)m, off); m = o > m ? o : m; }
;                 if (k0 == m) k0 = 0u; if (k1 == m) k1 = 0u;
;                 if (lane == 0) selq[tt * 16 + it] = 127 - (int)(m & 127u);
.LBB0_1094:
	s_waitcnt lgkmcnt(0)
	s_cmp_gt_i32 s18, 15
	s_cbranch_scc0 .Ltopk_small_q1
	s_lshl_b32 s19, s80, 10
	s_add_i32 s19, s19, 56384
	v_lshlrev_b32_e32 v82, 4, v184
	v_add_u32_e32 v82, s19, v82
	v_add_u32_e32 v83, 0xfffffffc, v82
	v_sub_u32_e32 v80, 127, v184
	v_sub_u32_e32 v81, 63, v184
	s_mov_b32 s54, 0xffffff80
	s_add_i32 s21, s18, -2
	v_add_u32_e32 v84, 64, v184
	ds_read_b32 v40, v83 offset:0
	ds_read_b128 v[48:51], v82 offset:0
	ds_read_b32 v41, v83 offset:1024
	ds_read_b128 v[52:55], v82 offset:1024
	ds_read_b32 v42, v83 offset:2048
	ds_read_b128 v[56:59], v82 offset:2048
	ds_read_b32 v43, v83 offset:3072
	ds_read_b128 v[60:63], v82 offset:3072
	s_waitcnt lgkmcnt(6)
	v_add_f32_e32 v40, v40, v48
	v_add_f32_e32 v40, v40, v49
	v_add_f32_e32 v40, v40, v50
	v_add_f32_e32 v40, v40, v51
	v_and_or_b32 v20, v40, s54, v80
	s_waitcnt lgkmcnt(4)
	v_add_f32_e32 v41, v41, v52
	v_add_f32_e32 v41, v41, v53
	v_add_f32_e32 v41, v41, v54
	v_add_f32_e32 v41, v41, v55
	v_and_or_b32 v24, v41, s54, v81
	s_waitcnt lgkmcnt(2)
	v_add_f32_e32 v42, v42, v56
	v_add_f32_e32 v42, v42, v57
	v_add_f32_e32 v42, v42, v58
	v_add_f32_e32 v42, v42, v59
	v_and_or_b32 v21, v42, s54, v80
	s_waitcnt lgkmcnt(0)
	v_add_f32_e32 v43, v43, v60
	v_add_f32_e32 v43, v43, v61
	v_add_f32_e32 v43, v43, v62
	v_add_f32_e32 v43, v43, v63
	v_and_or_b32 v25, v43, s54, v81
	ds_read_b32 v44, v83 offset:4096
	ds_read_b128 v[64:67], v82 offset:4096
	ds_read_b32 v45, v83 offset:5120
	ds_read_b128 v[68:71], v82 offset:5120
	ds_read_b32 v46, v83 offset:6144
	ds_read_b128 v[72:75], v82 offset:6144
	ds_read_b32 v47, v83 offset:7168
	ds_read_b128 v[76:79], v82 offset:7168
	s_waitcnt lgkmcnt(6)
	v_add_f32_e32 v44, v44, v64
	v_add_f32_e32 v44, v44, v65
	v_add_f32_e32 v44, v44, v66
	v_add_f32_e32 v44, v44, v67
	v_and_or_b32 v22, v44, s54, v80
	s_waitcnt lgkmcnt(4)
	v_add_f32_e32 v45, v45, v68
	v_add_f32_e32 v45, v45, v69
	v_add_f32_e32 v45, v45, v70
	v_add_f32_e32 v45, v45, v71
	v_and_or_b32 v26, v45, s54, v81
	s_waitcnt lgkmcnt(2)
	v_add_f32_e32 v46, v46, v72
	v_add_f32_e32 v46, v46, v73
	v_add_f32_e32 v46, v46, v74
	v_add_f32_e32 v46, v46, v75
	v_and_or_b32 v23, v46, s54, v80
	s_waitcnt lgkmcnt(0)
	v_add_f32_e32 v47, v47, v76
	v_add_f32_e32 v47, v47, v77
	v_add_f32_e32 v47, v47, v78
	v_add_f32_e32 v47, v47, v79
	v_and_or_b32 v27, v47, s54, v81
	v_cmp_le_i32_e64 s[14:15], v184, s21
	v_cmp_lt_i32_e64 s[34:35], 0, v184
	s_nop 0
	s_and_b64 s[14:15], s[14:15], s[34:35]
	v_cmp_le_i32_e64 s[34:35], v84, s21
	v_cndmask_b32_e64 v20, 0, v20, s[14:15]
	s_nop 0
	v_cndmask_b32_e64 v24, 0, v24, s[34:35]
	v_mov_b32_e32 v36, 0
	v_cndmask_b32_e64 v21, 0, v21, s[14:15]
	v_cndmask_b32_e64 v25, 0, v25, s[34:35]
	v_mov_b32_e32 v37, 0
	v_cndmask_b32_e64 v22, 0, v22, s[14:15]
	v_cndmask_b32_e64 v26, 0, v26, s[34:35]
	v_mov_b32_e32 v38, 0
	v_cndmask_b32_e64 v23, 0, v23, s[14:15]
	v_cndmask_b32_e64 v27, 0, v27, s[34:35]
	v_mov_b32_e32 v39, 0
	v_max_u32_e32 v28, v20, v24
	v_max_u32_e32 v29, v21, v25
	v_max_u32_e32 v30, v22, v26
	v_max_u32_e32 v31, v23, v27
	v_max_u32_dpp v28, v28, v28 quad_perm:[1,0,3,2] row_mask:0xf bank_mask:0xf
	v_max_u32_dpp v29, v29, v29 quad_perm:[1,0,3,2] row_mask:0xf bank_mask:0xf
	v_max_u32_dpp v30, v30, v30 quad_perm:[1,0,3,2] row_mask:0xf bank_mask:0xf
	v_max_u32_dpp v31, v31, v31 quad_perm:[1,0,3,2] row_mask:0xf bank_mask:0xf
	v_max_u32_dpp v28, v28, v28 quad_perm:[2,3,0,1] row_mask:0xf bank_mask:0xf
	v_max_u32_dpp v29, v29, v29 quad_perm:[2,3,0,1] row_mask:0xf bank_mask:0xf
	v_max_u32_dpp v30, v30, v30 quad_perm:[2,3,0,1] row_mask:0xf bank_mask:0xf
	v_max_u32_dpp v31, v31, v31 quad_perm:[2,3,0,1] row_mask:0xf bank_mask:0xf
	v_max_u32_dpp v28, v28, v28 row_half_mirror row_mask:0xf bank_mask:0xf
	v_max_u32_dpp v29, v29, v29 row_half_mirror row_mask:0xf bank_mask:0xf
	v_max_u32_dpp v30, v30, v30 row_half_mirror row_mask:0xf bank_mask:0xf
	v_max_u32_dpp v31, v31, v31 row_half_mirror row_mask:0xf bank_mask:0xf
	v_max_u32_dpp v28, v28, v28 row_mirror row_mask:0xf bank_mask:0xf
	v_max_u32_dpp v29, v29, v29 row_mirror row_mask:0xf bank_mask:0xf
	v_max_u32_dpp v30, v30, v30 row_mirror row_mask:0xf bank_mask:0xf
	v_max_u32_dpp v31, v31, v31 row_mirror row_mask:0xf bank_mask:0xf
	ds_swizzle_b32 v32, v28 offset:0x401f
	ds_swizzle_b32 v33, v29 offset:0x401f
	ds_swizzle_b32 v34, v30 offset:0x401f
	ds_swizzle_b32 v35, v31 offset:0x401f
	s_waitcnt lgkmcnt(3)
	v_max_u32_e32 v28, v28, v32
	s_waitcnt lgkmcnt(2)
	v_max_u32_e32 v29, v29, v33
	s_waitcnt lgkmcnt(1)
	v_max_u32_e32 v30, v30, v34
	s_waitcnt lgkmcnt(0)
; __device__ __forceinline__ void nsa_quad_pre(int bg, int quad, const bf16_t* Q, const bf16_t* KV, const bf16_t* KCMP, const bf16_t* VCMPT, const float* GN, bf16_t* ONSA, ...
;     ...
;             for (int it = 0; it < 13; ++it) {
;                 unsigned m = k0 > k1 ? k0 : k1;
; #pragma unroll
;                 for (int off = 32; off >= 1; off >>= 1) { const unsigned o = (unsigned)__shfl_xor((int)m, off); m = o > m ? o : m; }
;                 if (k0 == m) k0 = 0u; if (k1 == m) k1 = 0u;
;                 if (lane == 0) selq[tt * 16 + it] = 127 - (int)(m & 127u);
	v_max_u32_e32 v31, v31, v35
	v_mov_b32_e32 v32, v28
	v_mov_b32_e32 v33, v29
	v_mov_b32_e32 v34, v30
	v_mov_b32_e32 v35, v31
	v_permlane32_swap_b32_e32 v28, v32
	v_permlane32_swap_b32_e32 v29, v33
	v_permlane32_swap_b32_e32 v30, v34
	v_permlane32_swap_b32_e32 v31, v35
	v_max_u32_e32 v28, v28, v32
	v_max_u32_e32 v29, v29, v33
	v_max_u32_e32 v30, v30, v34
	v_max_u32_e32 v31, v31, v35
	v_cmp_eq_u32_e64 s[0:1], 0, v184
	v_and_b32_e32 v84, 127, v28
	v_sub_u32_e32 v84, 127, v84
	v_and_b32_e32 v85, 127, v29
	v_sub_u32_e32 v85, 127, v85
	v_and_b32_e32 v86, 127, v30
	v_sub_u32_e32 v86, 127, v86
	v_and_b32_e32 v87, 127, v31
	v_sub_u32_e32 v87, 127, v87
	v_cndmask_b32_e64 v36, v36, v84, s[0:1]
	v_cndmask_b32_e64 v37, v37, v85, s[0:1]
	v_cndmask_b32_e64 v38, v38, v86, s[0:1]
	v_cndmask_b32_e64 v39, v39, v87, s[0:1]
	v_cmp_eq_u32_e64 s[14:15], v28, v20
	v_cmp_eq_u32_e64 s[34:35], v28, v24
	v_cmp_eq_u32_e64 s[42:43], v29, v21
	v_cmp_eq_u32_e64 s[66:67], v29, v25
	v_cndmask_b32_e64 v20, v20, 0, s[14:15]
	v_cndmask_b32_e64 v24, v24, 0, s[34:35]
	v_cndmask_b32_e64 v21, v21, 0, s[42:43]
	v_cndmask_b32_e64 v25, v25, 0, s[66:67]
	v_cmp_eq_u32_e64 s[14:15], v30, v22
	v_cmp_eq_u32_e64 s[34:35], v30, v26
	v_cmp_eq_u32_e64 s[42:43], v31, v23
	v_cmp_eq_u32_e64 s[66:67], v31, v27
	v_cndmask_b32_e64 v22, v22, 0, s[14:15]
	v_cndmask_b32_e64 v26, v26, 0, s[34:35]
	v_cndmask_b32_e64 v23, v23, 0, s[42:43]
	v_cndmask_b32_e64 v27, v27, 0, s[66:67]
	v_max_u32_e32 v28, v20, v24
	v_max_u32_e32 v29, v21, v25
	v_max_u32_e32 v30, v22, v26
	v_max_u32_e32 v31, v23, v27
	v_max_u32_dpp v28, v28, v28 quad_perm:[1,0,3,2] row_mask:0xf bank_mask:0xf
	v_max_u32_dpp v29, v29, v29 quad_perm:[1,0,3,2] row_mask:0xf bank_mask:0xf
	v_max_u32_dpp v30, v30, v30 quad_perm:[1,0,3,2] row_mask:0xf bank_mask:0xf
	v_max_u32_dpp v31, v31, v31 quad_perm:[1,0,3,2] row_mask:0xf bank_mask:0xf
	v_max_u32_dpp v28, v28, v28 quad_perm:[2,3,0,1] row_mask:0xf bank_mask:0xf
	v_max_u32_dpp v29, v29, v29 quad_perm:[2,3,0,1] row_mask:0xf bank_mask:0xf
	v_max_u32_dpp v30, v30, v30 quad_perm:[2,3,0,1] row_mask:0xf bank_mask:0xf
	v_max_u32_dpp v31, v31, v31 quad_perm:[2,3,0,1] row_mask:0xf bank_mask:0xf
	v_max_u32_dpp v28, v28, v28 row_half_mirror row_mask:0xf bank_mask:0xf
	v_max_u32_dpp v29, v29, v29 row_half_mirror row_mask:0xf bank_mask:0xf
	v_max_u32_dpp v30, v30, v30 row_half_mirror row_mask:0xf bank_mask:0xf
	v_max_u32_dpp v31, v31, v31 row_half_mirror row_mask:0xf bank_mask:0xf
	v_max_u32_dpp v28, v28, v28 row_mirror row_mask:0xf bank_mask:0xf
	v_max_u32_dpp v29, v29, v29 row_mirror row_mask:0xf bank_mask:0xf
	v_max_u32_dpp v30, v30, v30 row_mirror row_mask:0xf bank_mask:0xf
	v_max_u32_dpp v31, v31, v31 row_mirror row_mask:0xf bank_mask:0xf
	ds_swizzle_b32 v32, v28 offset:0x401f
	ds_swizzle_b32 v33, v29 offset:0x401f
	ds_swizzle_b32 v34, v30 offset:0x401f
	ds_swizzle_b32 v35, v31 offset:0x401f
	s_waitcnt lgkmcnt(3)
	v_max_u32_e32 v28, v28, v32
	s_waitcnt lgkmcnt(2)
	v_max_u32_e32 v29, v29, v33
	s_waitcnt lgkmcnt(1)
	v_max_u32_e32 v30, v30, v34
	s_waitcnt lgkmcnt(0)
	v_max_u32_e32 v31, v31, v35
	v_mov_b32_e32 v32, v28
	v_mov_b32_e32 v33, v29
	v_mov_b32_e32 v34, v30
	v_mov_b32_e32 v35, v31
	v_permlane32_swap_b32_e32 v28, v32
	v_permlane32_swap_b32_e32 v29, v33
	v_permlane32_swap_b32_e32 v30, v34
	v_permlane32_swap_b32_e32 v31, v35
	v_max_u32_e32 v28, v28, v32
	v_max_u32_e32 v29, v29, v33
	v_max_u32_e32 v30, v30, v34
	v_max_u32_e32 v31, v31, v35
	v_cmp_eq_u32_e64 s[0:1], 1, v184
	v_and_b32_e32 v84, 127, v28
	v_sub_u32_e32 v84, 127, v84
	v_and_b32_e32 v85, 127, v29
	v_sub_u32_e32 v85, 127, v85
	v_and_b32_e32 v86, 127, v30
	v_sub_u32_e32 v86, 127, v86
	v_and_b32_e32 v87, 127, v31
	v_sub_u32_e32 v87, 127, v87
	v_cndmask_b32_e64 v36, v36, v84, s[0:1]
	v_cndmask_b32_e64 v37, v37, v85, s[0:1]
	v_cndmask_b32_e64 v38, v38, v86, s[0:1]
	v_cndmask_b32_e64 v39, v39, v87, s[0:1]
	v_cmp_eq_u32_e64 s[14:15], v28, v20
	v_cmp_eq_u32_e64 s[34:35], v28, v24
	v_cmp_eq_u32_e64 s[42:43], v29, v21
	v_cmp_eq_u32_e64 s[66:67], v29, v25
	v_cndmask_b32_e64 v20, v20, 0, s[14:15]
	v_cndmask_b32_e64 v24, v24, 0, s[34:35]
	v_cndmask_b32_e64 v21, v21, 0, s[42:43]
	v_cndmask_b32_e64 v25, v25, 0, s[66:67]
	v_cmp_eq_u32_e64 s[14:15], v30, v22
	v_cmp_eq_u32_e64 s[34:35], v30, v26
	v_cmp_eq_u32_e64 s[42:43], v31, v23
	v_cmp_eq_u32_e64 s[66:67], v31, v27
	v_cndmask_b32_e64 v22, v22, 0, s[14:15]
	v_cndmask_b32_e64 v26, v26, 0, s[34:35]
	v_cndmask_b32_e64 v23, v23, 0, s[42:43]
	v_cndmask_b32_e64 v27, v27, 0, s[66:67]
	v_max_u32_e32 v28, v20, v24
	v_max_u32_e32 v29, v21, v25
	v_max_u32_e32 v30, v22, v26
	v_max_u32_e32 v31, v23, v27
	v_max_u32_dpp v28, v28, v28 quad_perm:[1,0,3,2] row_mask:0xf bank_mask:0xf
	v_max_u32_dpp v29, v29, v29 quad_perm:[1,0,3,2] row_mask:0xf bank_mask:0xf
	v_max_u32_dpp v30, v30, v30 quad_perm:[1,0,3,2] row_mask:0xf bank_mask:0xf
	v_max_u32_dpp v31, v31, v31 quad_perm:[1,0,3,2] row_mask:0xf bank_mask:0xf
	v_max_u32_dpp v28, v28, v28 quad_perm:[2,3,0,1] row_mask:0xf bank_mask:0xf
	v_max_u32_dpp v29, v29, v29 quad_perm:[2,3,0,1] row_mask:0xf bank_mask:0xf
	v_max_u32_dpp v30, v30, v30 quad_perm:[2,3,0,1] row_mask:0xf bank_mask:0xf
	v_max_u32_dpp v31, v31, v31 quad_perm:[2,3,0,1] row_mask:0xf bank_mask:0xf
	v_max_u32_dpp v28, v28, v28 row_half_mirror row_mask:0xf bank_mask:0xf
	v_max_u32_dpp v29, v29, v29 row_half_mirror row_mask:0xf bank_mask:0xf
	v_max_u32_dpp v30, v30, v30 row_half_mirror row_mask:0xf bank_mask:0xf
	v_max_u32_dpp v31, v31, v31 row_half_mirror row_mask:0xf bank_mask:0xf
	v_max_u32_dpp v28, v28, v28 row_mirror row_mask:0xf bank_mask:0xf
	v_max_u32_dpp v29, v29, v29 row_mirror row_mask:0xf bank_mask:0xf
	v_max_u32_dpp v30, v30, v30 row_mirror row_mask:0xf bank_mask:0xf
	v_max_u32_dpp v31, v31, v31 row_mirror row_mask:0xf bank_mask:0xf
	ds_swizzle_b32 v32, v28 offset:0x401f
	ds_swizzle_b32 v33, v29 offset:0x401f
	ds_swizzle_b32 v34, v30 offset:0x401f
	ds_swizzle_b32 v35, v31 offset:0x401f
	s_waitcnt lgkmcnt(3)
; __device__ __forceinline__ void nsa_quad_pre(int bg, int quad, const bf16_t* Q, const bf16_t* KV, const bf16_t* KCMP, const bf16_t* VCMPT, const float* GN, bf16_t* ONSA, ...
;     ...
;             for (int it = 0; it < 13; ++it) {
;                 unsigned m = k0 > k1 ? k0 : k1;
; #pragma unroll
;                 for (int off = 32; off >= 1; off >>= 1) { const unsigned o = (unsigned)__shfl_xor((int)m, off); m = o > m ? o : m; }
;                 if (k0 == m) k0 = 0u; if (k1 == m) k1 = 0u;
;                 if (lane == 0) selq[tt * 16 + it] = 127 - (int)(m & 127u);
	v_max_u32_e32 v28, v28, v32
	s_waitcnt lgkmcnt(2)
	v_max_u32_e32 v29, v29, v33
	s_waitcnt lgkmcnt(1)
	v_max_u32_e32 v30, v30, v34
	s_waitcnt lgkmcnt(0)
	v_max_u32_e32 v31, v31, v35
	v_mov_b32_e32 v32, v28
	v_mov_b32_e32 v33, v29
	v_mov_b32_e32 v34, v30
	v_mov_b32_e32 v35, v31
	v_permlane32_swap_b32_e32 v28, v32
	v_permlane32_swap_b32_e32 v29, v33
	v_permlane32_swap_b32_e32 v30, v34
	v_permlane32_swap_b32_e32 v31, v35
	v_max_u32_e32 v28, v28, v32
	v_max_u32_e32 v29, v29, v33
	v_max_u32_e32 v30, v30, v34
	v_max_u32_e32 v31, v31, v35
	v_cmp_eq_u32_e64 s[0:1], 2, v184
	v_and_b32_e32 v84, 127, v28
	v_sub_u32_e32 v84, 127, v84
	v_and_b32_e32 v85, 127, v29
	v_sub_u32_e32 v85, 127, v85
	v_and_b32_e32 v86, 127, v30
	v_sub_u32_e32 v86, 127, v86
	v_and_b32_e32 v87, 127, v31
	v_sub_u32_e32 v87, 127, v87
	v_cndmask_b32_e64 v36, v36, v84, s[0:1]
	v_cndmask_b32_e64 v37, v37, v85, s[0:1]
	v_cndmask_b32_e64 v38, v38, v86, s[0:1]
	v_cndmask_b32_e64 v39, v39, v87, s[0:1]
	v_cmp_eq_u32_e64 s[14:15], v28, v20
	v_cmp_eq_u32_e64 s[34:35], v28, v24
	v_cmp_eq_u32_e64 s[42:43], v29, v21
	v_cmp_eq_u32_e64 s[66:67], v29, v25
	v_cndmask_b32_e64 v20, v20, 0, s[14:15]
	v_cndmask_b32_e64 v24, v24, 0, s[34:35]
	v_cndmask_b32_e64 v21, v21, 0, s[42:43]
	v_cndmask_b32_e64 v25, v25, 0, s[66:67]
	v_cmp_eq_u32_e64 s[14:15], v30, v22
	v_cmp_eq_u32_e64 s[34:35], v30, v26
	v_cmp_eq_u32_e64 s[42:43], v31, v23
	v_cmp_eq_u32_e64 s[66:67], v31, v27
	v_cndmask_b32_e64 v22, v22, 0, s[14:15]
	v_cndmask_b32_e64 v26, v26, 0, s[34:35]
	v_cndmask_b32_e64 v23, v23, 0, s[42:43]
	v_cndmask_b32_e64 v27, v27, 0, s[66:67]
	v_max_u32_e32 v28, v20, v24
	v_max_u32_e32 v29, v21, v25
	v_max_u32_e32 v30, v22, v26
	v_max_u32_e32 v31, v23, v27
	v_max_u32_dpp v28, v28, v28 quad_perm:[1,0,3,2] row_mask:0xf bank_mask:0xf
	v_max_u32_dpp v29, v29, v29 quad_perm:[1,0,3,2] row_mask:0xf bank_mask:0xf
	v_max_u32_dpp v30, v30, v30 quad_perm:[1,0,3,2] row_mask:0xf bank_mask:0xf
	v_max_u32_dpp v31, v31, v31 quad_perm:[1,0,3,2] row_mask:0xf bank_mask:0xf
	v_max_u32_dpp v28, v28, v28 quad_perm:[2,3,0,1] row_mask:0xf bank_mask:0xf
	v_max_u32_dpp v29, v29, v29 quad_perm:[2,3,0,1] row_mask:0xf bank_mask:0xf
	v_max_u32_dpp v30, v30, v30 quad_perm:[2,3,0,1] row_mask:0xf bank_mask:0xf
	v_max_u32_dpp v31, v31, v31 quad_perm:[2,3,0,1] row_mask:0xf bank_mask:0xf
	v_max_u32_dpp v28, v28, v28 row_half_mirror row_mask:0xf bank_mask:0xf
	v_max_u32_dpp v29, v29, v29 row_half_mirror row_mask:0xf bank_mask:0xf
	v_max_u32_dpp v30, v30, v30 row_half_mirror row_mask:0xf bank_mask:0xf
	v_max_u32_dpp v31, v31, v31 row_half_mirror row_mask:0xf bank_mask:0xf
	v_max_u32_dpp v28, v28, v28 row_mirror row_mask:0xf bank_mask:0xf
	v_max_u32_dpp v29, v29, v29 row_mirror row_mask:0xf bank_mask:0xf
	v_max_u32_dpp v30, v30, v30 row_mirror row_mask:0xf bank_mask:0xf
	v_max_u32_dpp v31, v31, v31 row_mirror row_mask:0xf bank_mask:0xf
	ds_swizzle_b32 v32, v28 offset:0x401f
	ds_swizzle_b32 v33, v29 offset:0x401f
	ds_swizzle_b32 v34, v30 offset:0x401f
	ds_swizzle_b32 v35, v31 offset:0x401f
	s_waitcnt lgkmcnt(3)
	v_max_u32_e32 v28, v28, v32
	s_waitcnt lgkmcnt(2)
	v_max_u32_e32 v29, v29, v33
	s_waitcnt lgkmcnt(1)
	v_max_u32_e32 v30, v30, v34
	s_waitcnt lgkmcnt(0)
	v_max_u32_e32 v31, v31, v35
	v_mov_b32_e32 v32, v28
	v_mov_b32_e32 v33, v29
	v_mov_b32_e32 v34, v30
	v_mov_b32_e32 v35, v31
	v_permlane32_swap_b32_e32 v28, v32
	v_permlane32_swap_b32_e32 v29, v33
	v_permlane32_swap_b32_e32 v30, v34
	v_permlane32_swap_b32_e32 v31, v35
	v_max_u32_e32 v28, v28, v32
	v_max_u32_e32 v29, v29, v33
	v_max_u32_e32 v30, v30, v34
	v_max_u32_e32 v31, v31, v35
	v_cmp_eq_u32_e64 s[0:1], 3, v184
	v_and_b32_e32 v84, 127, v28
	v_sub_u32_e32 v84, 127, v84
	v_and_b32_e32 v85, 127, v29
	v_sub_u32_e32 v85, 127, v85
	v_and_b32_e32 v86, 127, v30
	v_sub_u32_e32 v86, 127, v86
	v_and_b32_e32 v87, 127, v31
	v_sub_u32_e32 v87, 127, v87
	v_cndmask_b32_e64 v36, v36, v84, s[0:1]
	v_cndmask_b32_e64 v37, v37, v85, s[0:1]
	v_cndmask_b32_e64 v38, v38, v86, s[0:1]
	v_cndmask_b32_e64 v39, v39, v87, s[0:1]
	v_cmp_eq_u32_e64 s[14:15], v28, v20
	v_cmp_eq_u32_e64 s[34:35], v28, v24
	v_cmp_eq_u32_e64 s[42:43], v29, v21
	v_cmp_eq_u32_e64 s[66:67], v29, v25
	v_cndmask_b32_e64 v20, v20, 0, s[14:15]
	v_cndmask_b32_e64 v24, v24, 0, s[34:35]
	v_cndmask_b32_e64 v21, v21, 0, s[42:43]
	v_cndmask_b32_e64 v25, v25, 0, s[66:67]
	v_cmp_eq_u32_e64 s[14:15], v30, v22
	v_cmp_eq_u32_e64 s[34:35], v30, v26
	v_cmp_eq_u32_e64 s[42:43], v31, v23
	v_cmp_eq_u32_e64 s[66:67], v31, v27
	v_cndmask_b32_e64 v22, v22, 0, s[14:15]
	v_cndmask_b32_e64 v26, v26, 0, s[34:35]
	v_cndmask_b32_e64 v23, v23, 0, s[42:43]
	v_cndmask_b32_e64 v27, v27, 0, s[66:67]
	v_max_u32_e32 v28, v20, v24
	v_max_u32_e32 v29, v21, v25
	v_max_u32_e32 v30, v22, v26
	v_max_u32_e32 v31, v23, v27
	v_max_u32_dpp v28, v28, v28 quad_perm:[1,0,3,2] row_mask:0xf bank_mask:0xf
	v_max_u32_dpp v29, v29, v29 quad_perm:[1,0,3,2] row_mask:0xf bank_mask:0xf
	v_max_u32_dpp v30, v30, v30 quad_perm:[1,0,3,2] row_mask:0xf bank_mask:0xf
	v_max_u32_dpp v31, v31, v31 quad_perm:[1,0,3,2] row_mask:0xf bank_mask:0xf
	v_max_u32_dpp v28, v28, v28 quad_perm:[2,3,0,1] row_mask:0xf bank_mask:0xf
	v_max_u32_dpp v29, v29, v29 quad_perm:[2,3,0,1] row_mask:0xf bank_mask:0xf
	v_max_u32_dpp v30, v30, v30 quad_perm:[2,3,0,1] row_mask:0xf bank_mask:0xf
	v_max_u32_dpp v31, v31, v31 quad_perm:[2,3,0,1] row_mask:0xf bank_mask:0xf
	v_max_u32_dpp v28, v28, v28 row_half_mirror row_mask:0xf bank_mask:0xf
	v_max_u32_dpp v29, v29, v29 row_half_mirror row_mask:0xf bank_mask:0xf
	v_max_u32_dpp v30, v30, v30 row_half_mirror row_mask:0xf bank_mask:0xf
	v_max_u32_dpp v31, v31, v31 row_half_mirror row_mask:0xf bank_mask:0xf
	v_max_u32_dpp v28, v28, v28 row_mirror row_mask:0xf bank_mask:0xf
	v_max_u32_dpp v29, v29, v29 row_mirror row_mask:0xf bank_mask:0xf
	v_max_u32_dpp v30, v30, v30 row_mirror row_mask:0xf bank_mask:0xf
	v_max_u32_dpp v31, v31, v31 row_mirror row_mask:0xf bank_mask:0xf
	ds_swizzle_b32 v32, v28 offset:0x401f
	ds_swizzle_b32 v33, v29 offset:0x401f
	ds_swizzle_b32 v34, v30 offset:0x401f
	ds_swizzle_b32 v35, v31 offset:0x401f
	s_waitcnt lgkmcnt(3)
; __device__ __forceinline__ void nsa_quad_pre(int bg, int quad, const bf16_t* Q, const bf16_t* KV, const bf16_t* KCMP, const bf16_t* VCMPT, const float* GN, bf16_t* ONSA, ...
;     ...
;             for (int it = 0; it < 13; ++it) {
;                 unsigned m = k0 > k1 ? k0 : k1;
; #pragma unroll
;                 for (int off = 32; off >= 1; off >>= 1) { const unsigned o = (unsigned)__shfl_xor((int)m, off); m = o > m ? o : m; }
;                 if (k0 == m) k0 = 0u; if (k1 == m) k1 = 0u;
;                 if (lane == 0) selq[tt * 16 + it] = 127 - (int)(m & 127u);
	v_max_u32_e32 v28, v28, v32
	s_waitcnt lgkmcnt(2)
	v_max_u32_e32 v29, v29, v33
	s_waitcnt lgkmcnt(1)
	v_max_u32_e32 v30, v30, v34
	s_waitcnt lgkmcnt(0)
	v_max_u32_e32 v31, v31, v35
	v_mov_b32_e32 v32, v28
	v_mov_b32_e32 v33, v29
	v_mov_b32_e32 v34, v30
	v_mov_b32_e32 v35, v31
	v_permlane32_swap_b32_e32 v28, v32
	v_permlane32_swap_b32_e32 v29, v33
	v_permlane32_swap_b32_e32 v30, v34
	v_permlane32_swap_b32_e32 v31, v35
	v_max_u32_e32 v28, v28, v32
	v_max_u32_e32 v29, v29, v33
	v_max_u32_e32 v30, v30, v34
	v_max_u32_e32 v31, v31, v35
	v_cmp_eq_u32_e64 s[0:1], 4, v184
	v_and_b32_e32 v84, 127, v28
	v_sub_u32_e32 v84, 127, v84
	v_and_b32_e32 v85, 127, v29
	v_sub_u32_e32 v85, 127, v85
	v_and_b32_e32 v86, 127, v30
	v_sub_u32_e32 v86, 127, v86
	v_and_b32_e32 v87, 127, v31
	v_sub_u32_e32 v87, 127, v87
	v_cndmask_b32_e64 v36, v36, v84, s[0:1]
	v_cndmask_b32_e64 v37, v37, v85, s[0:1]
	v_cndmask_b32_e64 v38, v38, v86, s[0:1]
	v_cndmask_b32_e64 v39, v39, v87, s[0:1]
	v_cmp_eq_u32_e64 s[14:15], v28, v20
	v_cmp_eq_u32_e64 s[34:35], v28, v24
	v_cmp_eq_u32_e64 s[42:43], v29, v21
	v_cmp_eq_u32_e64 s[66:67], v29, v25
	v_cndmask_b32_e64 v20, v20, 0, s[14:15]
	v_cndmask_b32_e64 v24, v24, 0, s[34:35]
	v_cndmask_b32_e64 v21, v21, 0, s[42:43]
	v_cndmask_b32_e64 v25, v25, 0, s[66:67]
	v_cmp_eq_u32_e64 s[14:15], v30, v22
	v_cmp_eq_u32_e64 s[34:35], v30, v26
	v_cmp_eq_u32_e64 s[42:43], v31, v23
	v_cmp_eq_u32_e64 s[66:67], v31, v27
	v_cndmask_b32_e64 v22, v22, 0, s[14:15]
	v_cndmask_b32_e64 v26, v26, 0, s[34:35]
	v_cndmask_b32_e64 v23, v23, 0, s[42:43]
	v_cndmask_b32_e64 v27, v27, 0, s[66:67]
	v_max_u32_e32 v28, v20, v24
	v_max_u32_e32 v29, v21, v25
	v_max_u32_e32 v30, v22, v26
	v_max_u32_e32 v31, v23, v27
	v_max_u32_dpp v28, v28, v28 quad_perm:[1,0,3,2] row_mask:0xf bank_mask:0xf
	v_max_u32_dpp v29, v29, v29 quad_perm:[1,0,3,2] row_mask:0xf bank_mask:0xf
	v_max_u32_dpp v30, v30, v30 quad_perm:[1,0,3,2] row_mask:0xf bank_mask:0xf
	v_max_u32_dpp v31, v31, v31 quad_perm:[1,0,3,2] row_mask:0xf bank_mask:0xf
	v_max_u32_dpp v28, v28, v28 quad_perm:[2,3,0,1] row_mask:0xf bank_mask:0xf
	v_max_u32_dpp v29, v29, v29 quad_perm:[2,3,0,1] row_mask:0xf bank_mask:0xf
	v_max_u32_dpp v30, v30, v30 quad_perm:[2,3,0,1] row_mask:0xf bank_mask:0xf
	v_max_u32_dpp v31, v31, v31 quad_perm:[2,3,0,1] row_mask:0xf bank_mask:0xf
	v_max_u32_dpp v28, v28, v28 row_half_mirror row_mask:0xf bank_mask:0xf
	v_max_u32_dpp v29, v29, v29 row_half_mirror row_mask:0xf bank_mask:0xf
	v_max_u32_dpp v30, v30, v30 row_half_mirror row_mask:0xf bank_mask:0xf
	v_max_u32_dpp v31, v31, v31 row_half_mirror row_mask:0xf bank_mask:0xf
	v_max_u32_dpp v28, v28, v28 row_mirror row_mask:0xf bank_mask:0xf
	v_max_u32_dpp v29, v29, v29 row_mirror row_mask:0xf bank_mask:0xf
	v_max_u32_dpp v30, v30, v30 row_mirror row_mask:0xf bank_mask:0xf
	v_max_u32_dpp v31, v31, v31 row_mirror row_mask:0xf bank_mask:0xf
	ds_swizzle_b32 v32, v28 offset:0x401f
	ds_swizzle_b32 v33, v29 offset:0x401f
	ds_swizzle_b32 v34, v30 offset:0x401f
	ds_swizzle_b32 v35, v31 offset:0x401f
	s_waitcnt lgkmcnt(3)
	v_max_u32_e32 v28, v28, v32
	s_waitcnt lgkmcnt(2)
	v_max_u32_e32 v29, v29, v33
	s_waitcnt lgkmcnt(1)
	v_max_u32_e32 v30, v30, v34
	s_waitcnt lgkmcnt(0)
	v_max_u32_e32 v31, v31, v35
	v_mov_b32_e32 v32, v28
	v_mov_b32_e32 v33, v29
	v_mov_b32_e32 v34, v30
	v_mov_b32_e32 v35, v31
	v_permlane32_swap_b32_e32 v28, v32
	v_permlane32_swap_b32_e32 v29, v33
	v_permlane32_swap_b32_e32 v30, v34
	v_permlane32_swap_b32_e32 v31, v35
	v_max_u32_e32 v28, v28, v32
	v_max_u32_e32 v29, v29, v33
	v_max_u32_e32 v30, v30, v34
	v_max_u32_e32 v31, v31, v35
	v_cmp_eq_u32_e64 s[0:1], 5, v184
	v_and_b32_e32 v84, 127, v28
	v_sub_u32_e32 v84, 127, v84
	v_and_b32_e32 v85, 127, v29
	v_sub_u32_e32 v85, 127, v85
	v_and_b32_e32 v86, 127, v30
	v_sub_u32_e32 v86, 127, v86
	v_and_b32_e32 v87, 127, v31
	v_sub_u32_e32 v87, 127, v87
	v_cndmask_b32_e64 v36, v36, v84, s[0:1]
	v_cndmask_b32_e64 v37, v37, v85, s[0:1]
	v_cndmask_b32_e64 v38, v38, v86, s[0:1]
	v_cndmask_b32_e64 v39, v39, v87, s[0:1]
	v_cmp_eq_u32_e64 s[14:15], v28, v20
	v_cmp_eq_u32_e64 s[34:35], v28, v24
	v_cmp_eq_u32_e64 s[42:43], v29, v21
	v_cmp_eq_u32_e64 s[66:67], v29, v25
	v_cndmask_b32_e64 v20, v20, 0, s[14:15]
	v_cndmask_b32_e64 v24, v24, 0, s[34:35]
	v_cndmask_b32_e64 v21, v21, 0, s[42:43]
	v_cndmask_b32_e64 v25, v25, 0, s[66:67]
	v_cmp_eq_u32_e64 s[14:15], v30, v22
	v_cmp_eq_u32_e64 s[34:35], v30, v26
	v_cmp_eq_u32_e64 s[42:43], v31, v23
	v_cmp_eq_u32_e64 s[66:67], v31, v27
	v_cndmask_b32_e64 v22, v22, 0, s[14:15]
	v_cndmask_b32_e64 v26, v26, 0, s[34:35]
	v_cndmask_b32_e64 v23, v23, 0, s[42:43]
	v_cndmask_b32_e64 v27, v27, 0, s[66:67]
	v_max_u32_e32 v28, v20, v24
	v_max_u32_e32 v29, v21, v25
	v_max_u32_e32 v30, v22, v26
	v_max_u32_e32 v31, v23, v27
	v_max_u32_dpp v28, v28, v28 quad_perm:[1,0,3,2] row_mask:0xf bank_mask:0xf
	v_max_u32_dpp v29, v29, v29 quad_perm:[1,0,3,2] row_mask:0xf bank_mask:0xf
	v_max_u32_dpp v30, v30, v30 quad_perm:[1,0,3,2] row_mask:0xf bank_mask:0xf
	v_max_u32_dpp v31, v31, v31 quad_perm:[1,0,3,2] row_mask:0xf bank_mask:0xf
	v_max_u32_dpp v28, v28, v28 quad_perm:[2,3,0,1] row_mask:0xf bank_mask:0xf
	v_max_u32_dpp v29, v29, v29 quad_perm:[2,3,0,1] row_mask:0xf bank_mask:0xf
	v_max_u32_dpp v30, v30, v30 quad_perm:[2,3,0,1] row_mask:0xf bank_mask:0xf
	v_max_u32_dpp v31, v31, v31 quad_perm:[2,3,0,1] row_mask:0xf bank_mask:0xf
	v_max_u32_dpp v28, v28, v28 row_half_mirror row_mask:0xf bank_mask:0xf
	v_max_u32_dpp v29, v29, v29 row_half_mirror row_mask:0xf bank_mask:0xf
	v_max_u32_dpp v30, v30, v30 row_half_mirror row_mask:0xf bank_mask:0xf
	v_max_u32_dpp v31, v31, v31 row_half_mirror row_mask:0xf bank_mask:0xf
	v_max_u32_dpp v28, v28, v28 row_mirror row_mask:0xf bank_mask:0xf
	v_max_u32_dpp v29, v29, v29 row_mirror row_mask:0xf bank_mask:0xf
	v_max_u32_dpp v30, v30, v30 row_mirror row_mask:0xf bank_mask:0xf
	v_max_u32_dpp v31, v31, v31 row_mirror row_mask:0xf bank_mask:0xf
	ds_swizzle_b32 v32, v28 offset:0x401f
	ds_swizzle_b32 v33, v29 offset:0x401f
	ds_swizzle_b32 v34, v30 offset:0x401f
	ds_swizzle_b32 v35, v31 offset:0x401f
	s_waitcnt lgkmcnt(3)
; __device__ __forceinline__ void nsa_quad_pre(int bg, int quad, const bf16_t* Q, const bf16_t* KV, const bf16_t* KCMP, const bf16_t* VCMPT, const float* GN, bf16_t* ONSA, ...
;     ...
;             for (int it = 0; it < 13; ++it) {
;                 unsigned m = k0 > k1 ? k0 : k1;
; #pragma unroll
;                 for (int off = 32; off >= 1; off >>= 1) { const unsigned o = (unsigned)__shfl_xor((int)m, off); m = o > m ? o : m; }
;                 if (k0 == m) k0 = 0u; if (k1 == m) k1 = 0u;
;                 if (lane == 0) selq[tt * 16 + it] = 127 - (int)(m & 127u);
	v_max_u32_e32 v28, v28, v32
	s_waitcnt lgkmcnt(2)
	v_max_u32_e32 v29, v29, v33
	s_waitcnt lgkmcnt(1)
	v_max_u32_e32 v30, v30, v34
	s_waitcnt lgkmcnt(0)
	v_max_u32_e32 v31, v31, v35
	v_mov_b32_e32 v32, v28
	v_mov_b32_e32 v33, v29
	v_mov_b32_e32 v34, v30
	v_mov_b32_e32 v35, v31
	v_permlane32_swap_b32_e32 v28, v32
	v_permlane32_swap_b32_e32 v29, v33
	v_permlane32_swap_b32_e32 v30, v34
	v_permlane32_swap_b32_e32 v31, v35
	v_max_u32_e32 v28, v28, v32
	v_max_u32_e32 v29, v29, v33
	v_max_u32_e32 v30, v30, v34
	v_max_u32_e32 v31, v31, v35
	v_cmp_eq_u32_e64 s[0:1], 6, v184
	v_and_b32_e32 v84, 127, v28
	v_sub_u32_e32 v84, 127, v84
	v_and_b32_e32 v85, 127, v29
	v_sub_u32_e32 v85, 127, v85
	v_and_b32_e32 v86, 127, v30
	v_sub_u32_e32 v86, 127, v86
	v_and_b32_e32 v87, 127, v31
	v_sub_u32_e32 v87, 127, v87
	v_cndmask_b32_e64 v36, v36, v84, s[0:1]
	v_cndmask_b32_e64 v37, v37, v85, s[0:1]
	v_cndmask_b32_e64 v38, v38, v86, s[0:1]
	v_cndmask_b32_e64 v39, v39, v87, s[0:1]
	v_cmp_eq_u32_e64 s[14:15], v28, v20
	v_cmp_eq_u32_e64 s[34:35], v28, v24
	v_cmp_eq_u32_e64 s[42:43], v29, v21
	v_cmp_eq_u32_e64 s[66:67], v29, v25
	v_cndmask_b32_e64 v20, v20, 0, s[14:15]
	v_cndmask_b32_e64 v24, v24, 0, s[34:35]
	v_cndmask_b32_e64 v21, v21, 0, s[42:43]
	v_cndmask_b32_e64 v25, v25, 0, s[66:67]
	v_cmp_eq_u32_e64 s[14:15], v30, v22
	v_cmp_eq_u32_e64 s[34:35], v30, v26
	v_cmp_eq_u32_e64 s[42:43], v31, v23
	v_cmp_eq_u32_e64 s[66:67], v31, v27
	v_cndmask_b32_e64 v22, v22, 0, s[14:15]
	v_cndmask_b32_e64 v26, v26, 0, s[34:35]
	v_cndmask_b32_e64 v23, v23, 0, s[42:43]
	v_cndmask_b32_e64 v27, v27, 0, s[66:67]
	v_max_u32_e32 v28, v20, v24
	v_max_u32_e32 v29, v21, v25
	v_max_u32_e32 v30, v22, v26
	v_max_u32_e32 v31, v23, v27
	v_max_u32_dpp v28, v28, v28 quad_perm:[1,0,3,2] row_mask:0xf bank_mask:0xf
	v_max_u32_dpp v29, v29, v29 quad_perm:[1,0,3,2] row_mask:0xf bank_mask:0xf
	v_max_u32_dpp v30, v30, v30 quad_perm:[1,0,3,2] row_mask:0xf bank_mask:0xf
	v_max_u32_dpp v31, v31, v31 quad_perm:[1,0,3,2] row_mask:0xf bank_mask:0xf
	v_max_u32_dpp v28, v28, v28 quad_perm:[2,3,0,1] row_mask:0xf bank_mask:0xf
	v_max_u32_dpp v29, v29, v29 quad_perm:[2,3,0,1] row_mask:0xf bank_mask:0xf
	v_max_u32_dpp v30, v30, v30 quad_perm:[2,3,0,1] row_mask:0xf bank_mask:0xf
	v_max_u32_dpp v31, v31, v31 quad_perm:[2,3,0,1] row_mask:0xf bank_mask:0xf
	v_max_u32_dpp v28, v28, v28 row_half_mirror row_mask:0xf bank_mask:0xf
	v_max_u32_dpp v29, v29, v29 row_half_mirror row_mask:0xf bank_mask:0xf
	v_max_u32_dpp v30, v30, v30 row_half_mirror row_mask:0xf bank_mask:0xf
	v_max_u32_dpp v31, v31, v31 row_half_mirror row_mask:0xf bank_mask:0xf
	v_max_u32_dpp v28, v28, v28 row_mirror row_mask:0xf bank_mask:0xf
	v_max_u32_dpp v29, v29, v29 row_mirror row_mask:0xf bank_mask:0xf
	v_max_u32_dpp v30, v30, v30 row_mirror row_mask:0xf bank_mask:0xf
	v_max_u32_dpp v31, v31, v31 row_mirror row_mask:0xf bank_mask:0xf
	ds_swizzle_b32 v32, v28 offset:0x401f
	ds_swizzle_b32 v33, v29 offset:0x401f
	ds_swizzle_b32 v34, v30 offset:0x401f
	ds_swizzle_b32 v35, v31 offset:0x401f
	s_waitcnt lgkmcnt(3)
	v_max_u32_e32 v28, v28, v32
	s_waitcnt lgkmcnt(2)
	v_max_u32_e32 v29, v29, v33
	s_waitcnt lgkmcnt(1)
	v_max_u32_e32 v30, v30, v34
	s_waitcnt lgkmcnt(0)
	v_max_u32_e32 v31, v31, v35
	v_mov_b32_e32 v32, v28
	v_mov_b32_e32 v33, v29
	v_mov_b32_e32 v34, v30
	v_mov_b32_e32 v35, v31
	v_permlane32_swap_b32_e32 v28, v32
	v_permlane32_swap_b32_e32 v29, v33
	v_permlane32_swap_b32_e32 v30, v34
	v_permlane32_swap_b32_e32 v31, v35
	v_max_u32_e32 v28, v28, v32
	v_max_u32_e32 v29, v29, v33
	v_max_u32_e32 v30, v30, v34
	v_max_u32_e32 v31, v31, v35
	v_cmp_eq_u32_e64 s[0:1], 7, v184
	v_and_b32_e32 v84, 127, v28
	v_sub_u32_e32 v84, 127, v84
	v_and_b32_e32 v85, 127, v29
	v_sub_u32_e32 v85, 127, v85
	v_and_b32_e32 v86, 127, v30
	v_sub_u32_e32 v86, 127, v86
	v_and_b32_e32 v87, 127, v31
	v_sub_u32_e32 v87, 127, v87
	v_cndmask_b32_e64 v36, v36, v84, s[0:1]
	v_cndmask_b32_e64 v37, v37, v85, s[0:1]
	v_cndmask_b32_e64 v38, v38, v86, s[0:1]
	v_cndmask_b32_e64 v39, v39, v87, s[0:1]
	v_cmp_eq_u32_e64 s[14:15], v28, v20
	v_cmp_eq_u32_e64 s[34:35], v28, v24
	v_cmp_eq_u32_e64 s[42:43], v29, v21
	v_cmp_eq_u32_e64 s[66:67], v29, v25
	v_cndmask_b32_e64 v20, v20, 0, s[14:15]
	v_cndmask_b32_e64 v24, v24, 0, s[34:35]
	v_cndmask_b32_e64 v21, v21, 0, s[42:43]
	v_cndmask_b32_e64 v25, v25, 0, s[66:67]
	v_cmp_eq_u32_e64 s[14:15], v30, v22
	v_cmp_eq_u32_e64 s[34:35], v30, v26
	v_cmp_eq_u32_e64 s[42:43], v31, v23
	v_cmp_eq_u32_e64 s[66:67], v31, v27
	v_cndmask_b32_e64 v22, v22, 0, s[14:15]
	v_cndmask_b32_e64 v26, v26, 0, s[34:35]
	v_cndmask_b32_e64 v23, v23, 0, s[42:43]
	v_cndmask_b32_e64 v27, v27, 0, s[66:67]
	v_max_u32_e32 v28, v20, v24
	v_max_u32_e32 v29, v21, v25
	v_max_u32_e32 v30, v22, v26
	v_max_u32_e32 v31, v23, v27
	v_max_u32_dpp v28, v28, v28 quad_perm:[1,0,3,2] row_mask:0xf bank_mask:0xf
	v_max_u32_dpp v29, v29, v29 quad_perm:[1,0,3,2] row_mask:0xf bank_mask:0xf
	v_max_u32_dpp v30, v30, v30 quad_perm:[1,0,3,2] row_mask:0xf bank_mask:0xf
	v_max_u32_dpp v31, v31, v31 quad_perm:[1,0,3,2] row_mask:0xf bank_mask:0xf
	v_max_u32_dpp v28, v28, v28 quad_perm:[2,3,0,1] row_mask:0xf bank_mask:0xf
	v_max_u32_dpp v29, v29, v29 quad_perm:[2,3,0,1] row_mask:0xf bank_mask:0xf
	v_max_u32_dpp v30, v30, v30 quad_perm:[2,3,0,1] row_mask:0xf bank_mask:0xf
	v_max_u32_dpp v31, v31, v31 quad_perm:[2,3,0,1] row_mask:0xf bank_mask:0xf
	v_max_u32_dpp v28, v28, v28 row_half_mirror row_mask:0xf bank_mask:0xf
	v_max_u32_dpp v29, v29, v29 row_half_mirror row_mask:0xf bank_mask:0xf
	v_max_u32_dpp v30, v30, v30 row_half_mirror row_mask:0xf bank_mask:0xf
	v_max_u32_dpp v31, v31, v31 row_half_mirror row_mask:0xf bank_mask:0xf
	v_max_u32_dpp v28, v28, v28 row_mirror row_mask:0xf bank_mask:0xf
	v_max_u32_dpp v29, v29, v29 row_mirror row_mask:0xf bank_mask:0xf
	v_max_u32_dpp v30, v30, v30 row_mirror row_mask:0xf bank_mask:0xf
	v_max_u32_dpp v31, v31, v31 row_mirror row_mask:0xf bank_mask:0xf
	ds_swizzle_b32 v32, v28 offset:0x401f
	ds_swizzle_b32 v33, v29 offset:0x401f
	ds_swizzle_b32 v34, v30 offset:0x401f
	ds_swizzle_b32 v35, v31 offset:0x401f
	s_waitcnt lgkmcnt(3)
; __device__ __forceinline__ void nsa_quad_pre(int bg, int quad, const bf16_t* Q, const bf16_t* KV, const bf16_t* KCMP, const bf16_t* VCMPT, const float* GN, bf16_t* ONSA, ...
;     ...
;             for (int it = 0; it < 13; ++it) {
;                 unsigned m = k0 > k1 ? k0 : k1;
; #pragma unroll
;                 for (int off = 32; off >= 1; off >>= 1) { const unsigned o = (unsigned)__shfl_xor((int)m, off); m = o > m ? o : m; }
;                 if (k0 == m) k0 = 0u; if (k1 == m) k1 = 0u;
;                 if (lane == 0) selq[tt * 16 + it] = 127 - (int)(m & 127u);
	v_max_u32_e32 v28, v28, v32
	s_waitcnt lgkmcnt(2)
	v_max_u32_e32 v29, v29, v33
	s_waitcnt lgkmcnt(1)
	v_max_u32_e32 v30, v30, v34
	s_waitcnt lgkmcnt(0)
	v_max_u32_e32 v31, v31, v35
	v_mov_b32_e32 v32, v28
	v_mov_b32_e32 v33, v29
	v_mov_b32_e32 v34, v30
	v_mov_b32_e32 v35, v31
	v_permlane32_swap_b32_e32 v28, v32
	v_permlane32_swap_b32_e32 v29, v33
	v_permlane32_swap_b32_e32 v30, v34
	v_permlane32_swap_b32_e32 v31, v35
	v_max_u32_e32 v28, v28, v32
	v_max_u32_e32 v29, v29, v33
	v_max_u32_e32 v30, v30, v34
	v_max_u32_e32 v31, v31, v35
	v_cmp_eq_u32_e64 s[0:1], 8, v184
	v_and_b32_e32 v84, 127, v28
	v_sub_u32_e32 v84, 127, v84
	v_and_b32_e32 v85, 127, v29
	v_sub_u32_e32 v85, 127, v85
	v_and_b32_e32 v86, 127, v30
	v_sub_u32_e32 v86, 127, v86
	v_and_b32_e32 v87, 127, v31
	v_sub_u32_e32 v87, 127, v87
	v_cndmask_b32_e64 v36, v36, v84, s[0:1]
	v_cndmask_b32_e64 v37, v37, v85, s[0:1]
	v_cndmask_b32_e64 v38, v38, v86, s[0:1]
	v_cndmask_b32_e64 v39, v39, v87, s[0:1]
	v_cmp_eq_u32_e64 s[14:15], v28, v20
	v_cmp_eq_u32_e64 s[34:35], v28, v24
	v_cmp_eq_u32_e64 s[42:43], v29, v21
	v_cmp_eq_u32_e64 s[66:67], v29, v25
	v_cndmask_b32_e64 v20, v20, 0, s[14:15]
	v_cndmask_b32_e64 v24, v24, 0, s[34:35]
	v_cndmask_b32_e64 v21, v21, 0, s[42:43]
	v_cndmask_b32_e64 v25, v25, 0, s[66:67]
	v_cmp_eq_u32_e64 s[14:15], v30, v22
	v_cmp_eq_u32_e64 s[34:35], v30, v26
	v_cmp_eq_u32_e64 s[42:43], v31, v23
	v_cmp_eq_u32_e64 s[66:67], v31, v27
	v_cndmask_b32_e64 v22, v22, 0, s[14:15]
	v_cndmask_b32_e64 v26, v26, 0, s[34:35]
	v_cndmask_b32_e64 v23, v23, 0, s[42:43]
	v_cndmask_b32_e64 v27, v27, 0, s[66:67]
	v_max_u32_e32 v28, v20, v24
	v_max_u32_e32 v29, v21, v25
	v_max_u32_e32 v30, v22, v26
	v_max_u32_e32 v31, v23, v27
	v_max_u32_dpp v28, v28, v28 quad_perm:[1,0,3,2] row_mask:0xf bank_mask:0xf
	v_max_u32_dpp v29, v29, v29 quad_perm:[1,0,3,2] row_mask:0xf bank_mask:0xf
	v_max_u32_dpp v30, v30, v30 quad_perm:[1,0,3,2] row_mask:0xf bank_mask:0xf
	v_max_u32_dpp v31, v31, v31 quad_perm:[1,0,3,2] row_mask:0xf bank_mask:0xf
	v_max_u32_dpp v28, v28, v28 quad_perm:[2,3,0,1] row_mask:0xf bank_mask:0xf
	v_max_u32_dpp v29, v29, v29 quad_perm:[2,3,0,1] row_mask:0xf bank_mask:0xf
	v_max_u32_dpp v30, v30, v30 quad_perm:[2,3,0,1] row_mask:0xf bank_mask:0xf
	v_max_u32_dpp v31, v31, v31 quad_perm:[2,3,0,1] row_mask:0xf bank_mask:0xf
	v_max_u32_dpp v28, v28, v28 row_half_mirror row_mask:0xf bank_mask:0xf
	v_max_u32_dpp v29, v29, v29 row_half_mirror row_mask:0xf bank_mask:0xf
	v_max_u32_dpp v30, v30, v30 row_half_mirror row_mask:0xf bank_mask:0xf
	v_max_u32_dpp v31, v31, v31 row_half_mirror row_mask:0xf bank_mask:0xf
	v_max_u32_dpp v28, v28, v28 row_mirror row_mask:0xf bank_mask:0xf
	v_max_u32_dpp v29, v29, v29 row_mirror row_mask:0xf bank_mask:0xf
	v_max_u32_dpp v30, v30, v30 row_mirror row_mask:0xf bank_mask:0xf
	v_max_u32_dpp v31, v31, v31 row_mirror row_mask:0xf bank_mask:0xf
	ds_swizzle_b32 v32, v28 offset:0x401f
	ds_swizzle_b32 v33, v29 offset:0x401f
	ds_swizzle_b32 v34, v30 offset:0x401f
	ds_swizzle_b32 v35, v31 offset:0x401f
	s_waitcnt lgkmcnt(3)
	v_max_u32_e32 v28, v28, v32
	s_waitcnt lgkmcnt(2)
	v_max_u32_e32 v29, v29, v33
	s_waitcnt lgkmcnt(1)
	v_max_u32_e32 v30, v30, v34
	s_waitcnt lgkmcnt(0)
	v_max_u32_e32 v31, v31, v35
	v_mov_b32_e32 v32, v28
	v_mov_b32_e32 v33, v29
	v_mov_b32_e32 v34, v30
	v_mov_b32_e32 v35, v31
	v_permlane32_swap_b32_e32 v28, v32
	v_permlane32_swap_b32_e32 v29, v33
	v_permlane32_swap_b32_e32 v30, v34
	v_permlane32_swap_b32_e32 v31, v35
	v_max_u32_e32 v28, v28, v32
	v_max_u32_e32 v29, v29, v33
	v_max_u32_e32 v30, v30, v34
	v_max_u32_e32 v31, v31, v35
	v_cmp_eq_u32_e64 s[0:1], 9, v184
	v_and_b32_e32 v84, 127, v28
	v_sub_u32_e32 v84, 127, v84
	v_and_b32_e32 v85, 127, v29
	v_sub_u32_e32 v85, 127, v85
	v_and_b32_e32 v86, 127, v30
	v_sub_u32_e32 v86, 127, v86
	v_and_b32_e32 v87, 127, v31
	v_sub_u32_e32 v87, 127, v87
	v_cndmask_b32_e64 v36, v36, v84, s[0:1]
	v_cndmask_b32_e64 v37, v37, v85, s[0:1]
	v_cndmask_b32_e64 v38, v38, v86, s[0:1]
	v_cndmask_b32_e64 v39, v39, v87, s[0:1]
	v_cmp_eq_u32_e64 s[14:15], v28, v20
	v_cmp_eq_u32_e64 s[34:35], v28, v24
	v_cmp_eq_u32_e64 s[42:43], v29, v21
	v_cmp_eq_u32_e64 s[66:67], v29, v25
	v_cndmask_b32_e64 v20, v20, 0, s[14:15]
	v_cndmask_b32_e64 v24, v24, 0, s[34:35]
	v_cndmask_b32_e64 v21, v21, 0, s[42:43]
	v_cndmask_b32_e64 v25, v25, 0, s[66:67]
	v_cmp_eq_u32_e64 s[14:15], v30, v22
	v_cmp_eq_u32_e64 s[34:35], v30, v26
	v_cmp_eq_u32_e64 s[42:43], v31, v23
	v_cmp_eq_u32_e64 s[66:67], v31, v27
	v_cndmask_b32_e64 v22, v22, 0, s[14:15]
	v_cndmask_b32_e64 v26, v26, 0, s[34:35]
	v_cndmask_b32_e64 v23, v23, 0, s[42:43]
	v_cndmask_b32_e64 v27, v27, 0, s[66:67]
	v_max_u32_e32 v28, v20, v24
	v_max_u32_e32 v29, v21, v25
	v_max_u32_e32 v30, v22, v26
	v_max_u32_e32 v31, v23, v27
	v_max_u32_dpp v28, v28, v28 quad_perm:[1,0,3,2] row_mask:0xf bank_mask:0xf
	v_max_u32_dpp v29, v29, v29 quad_perm:[1,0,3,2] row_mask:0xf bank_mask:0xf
	v_max_u32_dpp v30, v30, v30 quad_perm:[1,0,3,2] row_mask:0xf bank_mask:0xf
	v_max_u32_dpp v31, v31, v31 quad_perm:[1,0,3,2] row_mask:0xf bank_mask:0xf
	v_max_u32_dpp v28, v28, v28 quad_perm:[2,3,0,1] row_mask:0xf bank_mask:0xf
	v_max_u32_dpp v29, v29, v29 quad_perm:[2,3,0,1] row_mask:0xf bank_mask:0xf
	v_max_u32_dpp v30, v30, v30 quad_perm:[2,3,0,1] row_mask:0xf bank_mask:0xf
	v_max_u32_dpp v31, v31, v31 quad_perm:[2,3,0,1] row_mask:0xf bank_mask:0xf
	v_max_u32_dpp v28, v28, v28 row_half_mirror row_mask:0xf bank_mask:0xf
	v_max_u32_dpp v29, v29, v29 row_half_mirror row_mask:0xf bank_mask:0xf
	v_max_u32_dpp v30, v30, v30 row_half_mirror row_mask:0xf bank_mask:0xf
	v_max_u32_dpp v31, v31, v31 row_half_mirror row_mask:0xf bank_mask:0xf
	v_max_u32_dpp v28, v28, v28 row_mirror row_mask:0xf bank_mask:0xf
	v_max_u32_dpp v29, v29, v29 row_mirror row_mask:0xf bank_mask:0xf
	v_max_u32_dpp v30, v30, v30 row_mirror row_mask:0xf bank_mask:0xf
	v_max_u32_dpp v31, v31, v31 row_mirror row_mask:0xf bank_mask:0xf
	ds_swizzle_b32 v32, v28 offset:0x401f
	ds_swizzle_b32 v33, v29 offset:0x401f
	ds_swizzle_b32 v34, v30 offset:0x401f
	ds_swizzle_b32 v35, v31 offset:0x401f
	s_waitcnt lgkmcnt(3)
; __device__ __forceinline__ void nsa_quad_pre(int bg, int quad, const bf16_t* Q, const bf16_t* KV, const bf16_t* KCMP, const bf16_t* VCMPT, const float* GN, bf16_t* ONSA, ...
;     ...
;             for (int it = 0; it < 13; ++it) {
;                 unsigned m = k0 > k1 ? k0 : k1;
; #pragma unroll
;                 for (int off = 32; off >= 1; off >>= 1) { const unsigned o = (unsigned)__shfl_xor((int)m, off); m = o > m ? o : m; }
;                 if (k0 == m) k0 = 0u; if (k1 == m) k1 = 0u;
;                 if (lane == 0) selq[tt * 16 + it] = 127 - (int)(m & 127u);
	v_max_u32_e32 v28, v28, v32
	s_waitcnt lgkmcnt(2)
	v_max_u32_e32 v29, v29, v33
	s_waitcnt lgkmcnt(1)
	v_max_u32_e32 v30, v30, v34
	s_waitcnt lgkmcnt(0)
	v_max_u32_e32 v31, v31, v35
	v_mov_b32_e32 v32, v28
	v_mov_b32_e32 v33, v29
	v_mov_b32_e32 v34, v30
	v_mov_b32_e32 v35, v31
	v_permlane32_swap_b32_e32 v28, v32
	v_permlane32_swap_b32_e32 v29, v33
	v_permlane32_swap_b32_e32 v30, v34
	v_permlane32_swap_b32_e32 v31, v35
	v_max_u32_e32 v28, v28, v32
	v_max_u32_e32 v29, v29, v33
	v_max_u32_e32 v30, v30, v34
	v_max_u32_e32 v31, v31, v35
	v_cmp_eq_u32_e64 s[0:1], 10, v184
	v_and_b32_e32 v84, 127, v28
	v_sub_u32_e32 v84, 127, v84
	v_and_b32_e32 v85, 127, v29
	v_sub_u32_e32 v85, 127, v85
	v_and_b32_e32 v86, 127, v30
	v_sub_u32_e32 v86, 127, v86
	v_and_b32_e32 v87, 127, v31
	v_sub_u32_e32 v87, 127, v87
	v_cndmask_b32_e64 v36, v36, v84, s[0:1]
	v_cndmask_b32_e64 v37, v37, v85, s[0:1]
	v_cndmask_b32_e64 v38, v38, v86, s[0:1]
	v_cndmask_b32_e64 v39, v39, v87, s[0:1]
	v_cmp_eq_u32_e64 s[14:15], v28, v20
	v_cmp_eq_u32_e64 s[34:35], v28, v24
	v_cmp_eq_u32_e64 s[42:43], v29, v21
	v_cmp_eq_u32_e64 s[66:67], v29, v25
	v_cndmask_b32_e64 v20, v20, 0, s[14:15]
	v_cndmask_b32_e64 v24, v24, 0, s[34:35]
	v_cndmask_b32_e64 v21, v21, 0, s[42:43]
	v_cndmask_b32_e64 v25, v25, 0, s[66:67]
	v_cmp_eq_u32_e64 s[14:15], v30, v22
	v_cmp_eq_u32_e64 s[34:35], v30, v26
	v_cmp_eq_u32_e64 s[42:43], v31, v23
	v_cmp_eq_u32_e64 s[66:67], v31, v27
	v_cndmask_b32_e64 v22, v22, 0, s[14:15]
	v_cndmask_b32_e64 v26, v26, 0, s[34:35]
	v_cndmask_b32_e64 v23, v23, 0, s[42:43]
	v_cndmask_b32_e64 v27, v27, 0, s[66:67]
	v_max_u32_e32 v28, v20, v24
	v_max_u32_e32 v29, v21, v25
	v_max_u32_e32 v30, v22, v26
	v_max_u32_e32 v31, v23, v27
	v_max_u32_dpp v28, v28, v28 quad_perm:[1,0,3,2] row_mask:0xf bank_mask:0xf
	v_max_u32_dpp v29, v29, v29 quad_perm:[1,0,3,2] row_mask:0xf bank_mask:0xf
	v_max_u32_dpp v30, v30, v30 quad_perm:[1,0,3,2] row_mask:0xf bank_mask:0xf
	v_max_u32_dpp v31, v31, v31 quad_perm:[1,0,3,2] row_mask:0xf bank_mask:0xf
	v_max_u32_dpp v28, v28, v28 quad_perm:[2,3,0,1] row_mask:0xf bank_mask:0xf
	v_max_u32_dpp v29, v29, v29 quad_perm:[2,3,0,1] row_mask:0xf bank_mask:0xf
	v_max_u32_dpp v30, v30, v30 quad_perm:[2,3,0,1] row_mask:0xf bank_mask:0xf
	v_max_u32_dpp v31, v31, v31 quad_perm:[2,3,0,1] row_mask:0xf bank_mask:0xf
	v_max_u32_dpp v28, v28, v28 row_half_mirror row_mask:0xf bank_mask:0xf
	v_max_u32_dpp v29, v29, v29 row_half_mirror row_mask:0xf bank_mask:0xf
	v_max_u32_dpp v30, v30, v30 row_half_mirror row_mask:0xf bank_mask:0xf
	v_max_u32_dpp v31, v31, v31 row_half_mirror row_mask:0xf bank_mask:0xf
	v_max_u32_dpp v28, v28, v28 row_mirror row_mask:0xf bank_mask:0xf
	v_max_u32_dpp v29, v29, v29 row_mirror row_mask:0xf bank_mask:0xf
	v_max_u32_dpp v30, v30, v30 row_mirror row_mask:0xf bank_mask:0xf
	v_max_u32_dpp v31, v31, v31 row_mirror row_mask:0xf bank_mask:0xf
	ds_swizzle_b32 v32, v28 offset:0x401f
	ds_swizzle_b32 v33, v29 offset:0x401f
	ds_swizzle_b32 v34, v30 offset:0x401f
	ds_swizzle_b32 v35, v31 offset:0x401f
	s_waitcnt lgkmcnt(3)
	v_max_u32_e32 v28, v28, v32
	s_waitcnt lgkmcnt(2)
	v_max_u32_e32 v29, v29, v33
	s_waitcnt lgkmcnt(1)
	v_max_u32_e32 v30, v30, v34
	s_waitcnt lgkmcnt(0)
; __device__ __forceinline__ void nsa_quad_pre(int bg, int quad, const bf16_t* Q, const bf16_t* KV, const bf16_t* KCMP, const bf16_t* VCMPT, const float* GN, bf16_t* ONSA, ...
;     ...
;             for (int it = 0; it < 13; ++it) {
;                 unsigned m = k0 > k1 ? k0 : k1;
; #pragma unroll
;                 for (int off = 32; off >= 1; off >>= 1) { const unsigned o = (unsigned)__shfl_xor((int)m, off); m = o > m ? o : m; }
;                 if (k0 == m) k0 = 0u; if (k1 == m) k1 = 0u;
;                 if (lane == 0) selq[tt * 16 + it] = 127 - (int)(m & 127u);
;             }
;             if (lane == 0) { selq[tt * 16 + 13] = 0; selq[tt * 16 + 14] = cur - 1; selq[tt * 16 + 15] = cur; }
	v_max_u32_e32 v31, v31, v35
	v_mov_b32_e32 v32, v28
	v_mov_b32_e32 v33, v29
	v_mov_b32_e32 v34, v30
	v_mov_b32_e32 v35, v31
	v_permlane32_swap_b32_e32 v28, v32
	v_permlane32_swap_b32_e32 v29, v33
	v_permlane32_swap_b32_e32 v30, v34
	v_permlane32_swap_b32_e32 v31, v35
	v_max_u32_e32 v28, v28, v32
	v_max_u32_e32 v29, v29, v33
	v_max_u32_e32 v30, v30, v34
	v_max_u32_e32 v31, v31, v35
	v_cmp_eq_u32_e64 s[0:1], 11, v184
	v_and_b32_e32 v84, 127, v28
	v_sub_u32_e32 v84, 127, v84
	v_and_b32_e32 v85, 127, v29
	v_sub_u32_e32 v85, 127, v85
	v_and_b32_e32 v86, 127, v30
	v_sub_u32_e32 v86, 127, v86
	v_and_b32_e32 v87, 127, v31
	v_sub_u32_e32 v87, 127, v87
	v_cndmask_b32_e64 v36, v36, v84, s[0:1]
	v_cndmask_b32_e64 v37, v37, v85, s[0:1]
	v_cndmask_b32_e64 v38, v38, v86, s[0:1]
	v_cndmask_b32_e64 v39, v39, v87, s[0:1]
	v_cmp_eq_u32_e64 s[14:15], v28, v20
	v_cmp_eq_u32_e64 s[34:35], v28, v24
	v_cmp_eq_u32_e64 s[42:43], v29, v21
	v_cmp_eq_u32_e64 s[66:67], v29, v25
	v_cndmask_b32_e64 v20, v20, 0, s[14:15]
	v_cndmask_b32_e64 v24, v24, 0, s[34:35]
	v_cndmask_b32_e64 v21, v21, 0, s[42:43]
	v_cndmask_b32_e64 v25, v25, 0, s[66:67]
	v_cmp_eq_u32_e64 s[14:15], v30, v22
	v_cmp_eq_u32_e64 s[34:35], v30, v26
	v_cmp_eq_u32_e64 s[42:43], v31, v23
	v_cmp_eq_u32_e64 s[66:67], v31, v27
	v_cndmask_b32_e64 v22, v22, 0, s[14:15]
	v_cndmask_b32_e64 v26, v26, 0, s[34:35]
	v_cndmask_b32_e64 v23, v23, 0, s[42:43]
	v_cndmask_b32_e64 v27, v27, 0, s[66:67]
	v_max_u32_e32 v28, v20, v24
	v_max_u32_e32 v29, v21, v25
	v_max_u32_e32 v30, v22, v26
	v_max_u32_e32 v31, v23, v27
	v_max_u32_dpp v28, v28, v28 quad_perm:[1,0,3,2] row_mask:0xf bank_mask:0xf
	v_max_u32_dpp v29, v29, v29 quad_perm:[1,0,3,2] row_mask:0xf bank_mask:0xf
	v_max_u32_dpp v30, v30, v30 quad_perm:[1,0,3,2] row_mask:0xf bank_mask:0xf
	v_max_u32_dpp v31, v31, v31 quad_perm:[1,0,3,2] row_mask:0xf bank_mask:0xf
	v_max_u32_dpp v28, v28, v28 quad_perm:[2,3,0,1] row_mask:0xf bank_mask:0xf
	v_max_u32_dpp v29, v29, v29 quad_perm:[2,3,0,1] row_mask:0xf bank_mask:0xf
	v_max_u32_dpp v30, v30, v30 quad_perm:[2,3,0,1] row_mask:0xf bank_mask:0xf
	v_max_u32_dpp v31, v31, v31 quad_perm:[2,3,0,1] row_mask:0xf bank_mask:0xf
	v_max_u32_dpp v28, v28, v28 row_half_mirror row_mask:0xf bank_mask:0xf
	v_max_u32_dpp v29, v29, v29 row_half_mirror row_mask:0xf bank_mask:0xf
	v_max_u32_dpp v30, v30, v30 row_half_mirror row_mask:0xf bank_mask:0xf
	v_max_u32_dpp v31, v31, v31 row_half_mirror row_mask:0xf bank_mask:0xf
	v_max_u32_dpp v28, v28, v28 row_mirror row_mask:0xf bank_mask:0xf
	v_max_u32_dpp v29, v29, v29 row_mirror row_mask:0xf bank_mask:0xf
	v_max_u32_dpp v30, v30, v30 row_mirror row_mask:0xf bank_mask:0xf
	v_max_u32_dpp v31, v31, v31 row_mirror row_mask:0xf bank_mask:0xf
	ds_swizzle_b32 v32, v28 offset:0x401f
	ds_swizzle_b32 v33, v29 offset:0x401f
	ds_swizzle_b32 v34, v30 offset:0x401f
	ds_swizzle_b32 v35, v31 offset:0x401f
	s_waitcnt lgkmcnt(3)
	v_max_u32_e32 v28, v28, v32
	s_waitcnt lgkmcnt(2)
	v_max_u32_e32 v29, v29, v33
	s_waitcnt lgkmcnt(1)
	v_max_u32_e32 v30, v30, v34
	s_waitcnt lgkmcnt(0)
	v_max_u32_e32 v31, v31, v35
	v_mov_b32_e32 v32, v28
	v_mov_b32_e32 v33, v29
	v_mov_b32_e32 v34, v30
	v_mov_b32_e32 v35, v31
	v_permlane32_swap_b32_e32 v28, v32
	v_permlane32_swap_b32_e32 v29, v33
	v_permlane32_swap_b32_e32 v30, v34
	v_permlane32_swap_b32_e32 v31, v35
	v_max_u32_e32 v28, v28, v32
	v_max_u32_e32 v29, v29, v33
	v_max_u32_e32 v30, v30, v34
	v_max_u32_e32 v31, v31, v35
	v_cmp_eq_u32_e64 s[0:1], 12, v184
	v_and_b32_e32 v84, 127, v28
	v_sub_u32_e32 v84, 127, v84
	v_and_b32_e32 v85, 127, v29
	v_sub_u32_e32 v85, 127, v85
	v_and_b32_e32 v86, 127, v30
	v_sub_u32_e32 v86, 127, v86
	v_and_b32_e32 v87, 127, v31
	v_sub_u32_e32 v87, 127, v87
	v_cndmask_b32_e64 v36, v36, v84, s[0:1]
	v_cndmask_b32_e64 v37, v37, v85, s[0:1]
	v_cndmask_b32_e64 v38, v38, v86, s[0:1]
	v_cndmask_b32_e64 v39, v39, v87, s[0:1]
	s_add_i32 s19, s18, -1
	v_mov_b32_e32 v84, s19
	v_mov_b32_e32 v85, s18
	v_cmp_eq_u32_e64 s[14:15], 14, v184
	v_cmp_eq_u32_e64 s[34:35], 15, v184
	s_nop 0
	v_cndmask_b32_e64 v36, v36, v84, s[14:15]
	v_cndmask_b32_e64 v36, v36, v85, s[34:35]
	v_cndmask_b32_e64 v37, v37, v84, s[14:15]
	v_cndmask_b32_e64 v37, v37, v85, s[34:35]
	v_cndmask_b32_e64 v38, v38, v84, s[14:15]
	v_cndmask_b32_e64 v38, v38, v85, s[34:35]
	v_cndmask_b32_e64 v39, v39, v84, s[14:15]
	v_cndmask_b32_e64 v39, v39, v85, s[34:35]
	s_and_saveexec_b64 s[42:43], s[6:7]
	ds_write_b32 v196, v36 offset:51520
	ds_write_b32 v196, v37 offset:51584
	ds_write_b32 v196, v38 offset:51648
	ds_write_b32 v196, v39 offset:51712
	s_or_b64 exec, exec, s[42:43]
	s_branch .Ltopk_done_q1
.Ltopk_small_q1:
	s_nop 1
	s_and_saveexec_b64 s[42:43], s[6:7]
	ds_write_b32 v196, v184 offset:51520
	ds_write_b32 v196, v184 offset:51584
	ds_write_b32 v196, v184 offset:51648
	ds_write_b32 v196, v184 offset:51712
	s_or_b64 exec, exec, s[42:43]
